# K-loop byte-phase pin: every 16-MFMA run starts at 0 mod 8 (s_nop pads in load segments)
# speedup vs baseline: 1.0070x; 1.0022x over previous
.LBB0_228:
	ds_read_b128 v[128:131], v179
	ds_read_b128 v[132:135], v179 offset:1024
	ds_read_b128 v[136:139], v179 offset:2048
	ds_read_b128 v[140:143], v179 offset:3072
	ds_read_b128 v[162:165], v180
	ds_read_b128 v[166:169], v180 offset:1024
	ds_read_b128 v[170:173], v180 offset:2048
	ds_read_b128 v[186:189], v180 offset:3072
	s_add_u32 s8, s6, 0x10000
	s_addc_u32 s9, s7, 0
	s_cmp_eq_u32 s92, 12
	s_cselect_b32 s80, s69, s8
	s_cselect_b32 s81, s18, s9
	s_cselect_b32 s12, s77, vcc_lo
	s_cselect_b32 s13, s71, vcc_hi
	s_add_u32 s10, s80, 0x8000
	s_addc_u32 s11, s81, 0
	s_add_i32 m0, s79, 0xc000
	ds_read_b128 v[190:193], v181
	ds_read_b128 v[194:197], v181 offset:1024
	ds_read_b128 v[198:201], v181 offset:2048
	ds_read_b128 v[202:205], v181 offset:3072
	ds_read_b128 v[206:209], v181 offset:4096
	ds_read_b128 v[210:213], v181 offset:5120
	ds_read_b128 v[214:217], v181 offset:6144
	ds_read_b128 v[218:221], v181 offset:7168
	global_load_lds_dwordx4 v154, s[6:7]
	s_add_i32 m0, s79, 0xe000
	s_nop 0
	global_load_lds_dwordx4 v156, s[6:7]
	s_nop 0
	s_waitcnt vmcnt(8)
	s_waitcnt lgkmcnt(0)
	s_barrier
	s_setprio 1
	s_waitcnt lgkmcnt(0)
	v_mfma_f32_16x16x32_bf16 v[124:127], v[128:131], v[190:193], v[124:127]
	v_mfma_f32_16x16x32_bf16 v[120:123], v[136:139], v[190:193], v[120:123]
	v_mfma_f32_16x16x32_bf16 v[108:111], v[128:131], v[198:201], v[108:111]
	v_mfma_f32_16x16x32_bf16 v[104:107], v[136:139], v[198:201], v[104:107]
	v_mfma_f32_16x16x32_bf16 v[92:95], v[128:131], v[206:209], v[92:95]
	v_mfma_f32_16x16x32_bf16 v[88:91], v[136:139], v[206:209], v[88:91]
	v_mfma_f32_16x16x32_bf16 v[76:79], v[128:131], v[214:217], v[76:79]
	v_mfma_f32_16x16x32_bf16 v[72:75], v[136:139], v[214:217], v[72:75]
	v_mfma_f32_16x16x32_bf16 v[124:127], v[132:135], v[194:197], v[124:127]
	v_mfma_f32_16x16x32_bf16 v[120:123], v[140:143], v[194:197], v[120:123]
	v_mfma_f32_16x16x32_bf16 v[108:111], v[132:135], v[202:205], v[108:111]
	v_mfma_f32_16x16x32_bf16 v[104:107], v[140:143], v[202:205], v[104:107]
	v_mfma_f32_16x16x32_bf16 v[92:95], v[132:135], v[210:213], v[92:95]
	v_mfma_f32_16x16x32_bf16 v[88:91], v[140:143], v[210:213], v[88:91]
	v_mfma_f32_16x16x32_bf16 v[76:79], v[132:135], v[218:221], v[76:79]
	v_mfma_f32_16x16x32_bf16 v[72:75], v[140:143], v[218:221], v[72:75]
	s_setprio 0
	s_setprio 1
	v_mfma_f32_16x16x32_bf16 v[116:119], v[162:165], v[190:193], v[116:119]
	v_mfma_f32_16x16x32_bf16 v[112:115], v[170:173], v[190:193], v[112:115]
	v_mfma_f32_16x16x32_bf16 v[100:103], v[162:165], v[198:201], v[100:103]
	v_mfma_f32_16x16x32_bf16 v[96:99], v[170:173], v[198:201], v[96:99]
	v_mfma_f32_16x16x32_bf16 v[84:87], v[162:165], v[206:209], v[84:87]
	v_mfma_f32_16x16x32_bf16 v[80:83], v[170:173], v[206:209], v[80:83]
	v_mfma_f32_16x16x32_bf16 v[68:71], v[162:165], v[214:217], v[68:71]
	v_mfma_f32_16x16x32_bf16 v[64:67], v[170:173], v[214:217], v[64:67]
	v_mfma_f32_16x16x32_bf16 v[116:119], v[166:169], v[194:197], v[116:119]
	v_mfma_f32_16x16x32_bf16 v[112:115], v[186:189], v[194:197], v[112:115]
	v_mfma_f32_16x16x32_bf16 v[100:103], v[166:169], v[202:205], v[100:103]
	v_mfma_f32_16x16x32_bf16 v[96:99], v[186:189], v[202:205], v[96:99]
	v_mfma_f32_16x16x32_bf16 v[84:87], v[166:169], v[210:213], v[84:87]
	v_mfma_f32_16x16x32_bf16 v[80:83], v[186:189], v[210:213], v[80:83]
	v_mfma_f32_16x16x32_bf16 v[68:71], v[166:169], v[218:221], v[68:71]
	v_mfma_f32_16x16x32_bf16 v[64:67], v[186:189], v[218:221], v[64:67]
	s_setprio 0
	s_barrier
	s_add_i32 s6, s34, s84
	s_mov_b32 m0, s6
	ds_read_b128 v[190:193], v181 offset:16384
	ds_read_b128 v[194:197], v181 offset:17408
	ds_read_b128 v[198:201], v181 offset:18432
	ds_read_b128 v[202:205], v181 offset:19456
	ds_read_b128 v[206:209], v181 offset:20480
	ds_read_b128 v[210:213], v181 offset:21504
	ds_read_b128 v[214:217], v181 offset:22528
	ds_read_b128 v[218:221], v181 offset:23552
	global_load_lds_dwordx4 v146, s[12:13]
	s_add_i32 m0, s6, 0x2000
	s_add_u32 s6, s12, 0x40000
	s_addc_u32 s7, s13, 0
	s_add_i32 s38, s35, s84
	global_load_lds_dwordx4 v150, s[12:13]
	s_mov_b32 m0, s38
	s_nop 0
	global_load_lds_dwordx4 v146, s[6:7]
	s_add_i32 m0, s38, 0x2000
	s_nop 0
	global_load_lds_dwordx4 v150, s[6:7]
	s_mov_b32 m0, s79
	s_nop 0
	global_load_lds_dwordx4 v144, s[80:81]
	s_mov_b32 m0, s85
	s_nop 0
	global_load_lds_dwordx4 v148, s[80:81]
	s_waitcnt vmcnt(8)
	s_waitcnt lgkmcnt(0)
	s_barrier
	s_setprio 1
	s_waitcnt lgkmcnt(0)
	v_mfma_f32_16x16x32_bf16 v[60:63], v[128:131], v[190:193], v[60:63]
	v_mfma_f32_16x16x32_bf16 v[56:59], v[136:139], v[190:193], v[56:59]
	v_mfma_f32_16x16x32_bf16 v[44:47], v[128:131], v[198:201], v[44:47]
	v_mfma_f32_16x16x32_bf16 v[40:43], v[136:139], v[198:201], v[40:43]
	v_mfma_f32_16x16x32_bf16 v[28:31], v[128:131], v[206:209], v[28:31]
	v_mfma_f32_16x16x32_bf16 v[24:27], v[136:139], v[206:209], v[24:27]
	v_mfma_f32_16x16x32_bf16 v[12:15], v[128:131], v[214:217], v[12:15]
	v_mfma_f32_16x16x32_bf16 v[8:11], v[136:139], v[214:217], v[8:11]
	v_mfma_f32_16x16x32_bf16 v[60:63], v[132:135], v[194:197], v[60:63]
	v_mfma_f32_16x16x32_bf16 v[56:59], v[140:143], v[194:197], v[56:59]
	v_mfma_f32_16x16x32_bf16 v[44:47], v[132:135], v[202:205], v[44:47]
	v_mfma_f32_16x16x32_bf16 v[40:43], v[140:143], v[202:205], v[40:43]
	v_mfma_f32_16x16x32_bf16 v[28:31], v[132:135], v[210:213], v[28:31]
	v_mfma_f32_16x16x32_bf16 v[24:27], v[140:143], v[210:213], v[24:27]
	v_mfma_f32_16x16x32_bf16 v[12:15], v[132:135], v[218:221], v[12:15]
	v_mfma_f32_16x16x32_bf16 v[8:11], v[140:143], v[218:221], v[8:11]
	s_setprio 0
	s_setprio 1
	v_mfma_f32_16x16x32_bf16 v[52:55], v[162:165], v[190:193], v[52:55]
	v_mfma_f32_16x16x32_bf16 v[48:51], v[170:173], v[190:193], v[48:51]
	v_mfma_f32_16x16x32_bf16 v[36:39], v[162:165], v[198:201], v[36:39]
	v_mfma_f32_16x16x32_bf16 v[32:35], v[170:173], v[198:201], v[32:35]
	v_mfma_f32_16x16x32_bf16 v[20:23], v[162:165], v[206:209], v[20:23]
	v_mfma_f32_16x16x32_bf16 v[16:19], v[170:173], v[206:209], v[16:19]
	v_mfma_f32_16x16x32_bf16 v[4:7], v[162:165], v[214:217], v[4:7]
	v_mfma_f32_16x16x32_bf16 v[0:3], v[170:173], v[214:217], v[0:3]
	v_mfma_f32_16x16x32_bf16 v[52:55], v[166:169], v[194:197], v[52:55]
	v_mfma_f32_16x16x32_bf16 v[48:51], v[186:189], v[194:197], v[48:51]
	v_mfma_f32_16x16x32_bf16 v[36:39], v[166:169], v[202:205], v[36:39]
	v_mfma_f32_16x16x32_bf16 v[32:35], v[186:189], v[202:205], v[32:35]
	v_mfma_f32_16x16x32_bf16 v[20:23], v[166:169], v[210:213], v[20:23]
	v_mfma_f32_16x16x32_bf16 v[16:19], v[186:189], v[210:213], v[16:19]
	v_mfma_f32_16x16x32_bf16 v[4:7], v[166:169], v[218:221], v[4:7]
	v_mfma_f32_16x16x32_bf16 v[0:3], v[186:189], v[218:221], v[0:3]
	s_setprio 0
	s_barrier
	s_add_i32 s38, 0, 0x18000
	s_add_i32 s39, 0, 0x1c000
	v_add_u32_e32 v140, s38, v178
	v_add_u32_e32 v152, s39, v178
	ds_read_b128 v[128:131], v140
	ds_read_b128 v[132:135], v140 offset:1024
	ds_read_b128 v[136:139], v140 offset:2048
	ds_read_b128 v[140:143], v140 offset:3072
	ds_read_b128 v[162:165], v152
	ds_read_b128 v[166:169], v152 offset:1024
	ds_read_b128 v[170:173], v152 offset:2048
	ds_read_b128 v[186:189], v152 offset:3072
	s_add_u32 s6, s80, 0x4000
	s_addc_u32 s7, s81, 0
	s_mov_b32 m0, s86
	ds_read_b128 v[190:193], v181 offset:32768
	ds_read_b128 v[194:197], v181 offset:33792
	ds_read_b128 v[198:201], v181 offset:34816
	ds_read_b128 v[202:205], v181 offset:35840
	ds_read_b128 v[206:209], v181 offset:36864
	ds_read_b128 v[210:213], v181 offset:37888
	ds_read_b128 v[214:217], v181 offset:38912
	ds_read_b128 v[218:221], v181 offset:39936
	global_load_lds_dwordx4 v144, s[6:7]
	s_mov_b32 m0, s87
	s_nop 0
	global_load_lds_dwordx4 v148, s[6:7]
	s_nop 0
	s_waitcnt vmcnt(8)
	s_waitcnt lgkmcnt(0)
	s_barrier
	s_setprio 1
	s_waitcnt lgkmcnt(0)
	v_mfma_f32_16x16x32_bf16 v[124:127], v[128:131], v[190:193], v[124:127]
	v_mfma_f32_16x16x32_bf16 v[120:123], v[136:139], v[190:193], v[120:123]
	v_mfma_f32_16x16x32_bf16 v[108:111], v[128:131], v[198:201], v[108:111]
	v_mfma_f32_16x16x32_bf16 v[104:107], v[136:139], v[198:201], v[104:107]
	v_mfma_f32_16x16x32_bf16 v[92:95], v[128:131], v[206:209], v[92:95]
	v_mfma_f32_16x16x32_bf16 v[88:91], v[136:139], v[206:209], v[88:91]
	v_mfma_f32_16x16x32_bf16 v[76:79], v[128:131], v[214:217], v[76:79]
	v_mfma_f32_16x16x32_bf16 v[72:75], v[136:139], v[214:217], v[72:75]
	v_mfma_f32_16x16x32_bf16 v[124:127], v[132:135], v[194:197], v[124:127]
	v_mfma_f32_16x16x32_bf16 v[120:123], v[140:143], v[194:197], v[120:123]
	v_mfma_f32_16x16x32_bf16 v[108:111], v[132:135], v[202:205], v[108:111]
	v_mfma_f32_16x16x32_bf16 v[104:107], v[140:143], v[202:205], v[104:107]
	v_mfma_f32_16x16x32_bf16 v[92:95], v[132:135], v[210:213], v[92:95]
	v_mfma_f32_16x16x32_bf16 v[88:91], v[140:143], v[210:213], v[88:91]
	v_mfma_f32_16x16x32_bf16 v[76:79], v[132:135], v[218:221], v[76:79]
	v_mfma_f32_16x16x32_bf16 v[72:75], v[140:143], v[218:221], v[72:75]
	s_setprio 0
	s_setprio 1
	v_mfma_f32_16x16x32_bf16 v[116:119], v[162:165], v[190:193], v[116:119]
	v_mfma_f32_16x16x32_bf16 v[112:115], v[170:173], v[190:193], v[112:115]
	v_mfma_f32_16x16x32_bf16 v[100:103], v[162:165], v[198:201], v[100:103]
	v_mfma_f32_16x16x32_bf16 v[96:99], v[170:173], v[198:201], v[96:99]
	v_mfma_f32_16x16x32_bf16 v[84:87], v[162:165], v[206:209], v[84:87]
	v_mfma_f32_16x16x32_bf16 v[80:83], v[170:173], v[206:209], v[80:83]
	v_mfma_f32_16x16x32_bf16 v[68:71], v[162:165], v[214:217], v[68:71]
	v_mfma_f32_16x16x32_bf16 v[64:67], v[170:173], v[214:217], v[64:67]
	v_mfma_f32_16x16x32_bf16 v[116:119], v[166:169], v[194:197], v[116:119]
	v_mfma_f32_16x16x32_bf16 v[112:115], v[186:189], v[194:197], v[112:115]
	v_mfma_f32_16x16x32_bf16 v[100:103], v[166:169], v[202:205], v[100:103]
	v_mfma_f32_16x16x32_bf16 v[96:99], v[186:189], v[202:205], v[96:99]
	v_mfma_f32_16x16x32_bf16 v[84:87], v[166:169], v[210:213], v[84:87]
	v_mfma_f32_16x16x32_bf16 v[80:83], v[186:189], v[210:213], v[80:83]
	v_mfma_f32_16x16x32_bf16 v[68:71], v[166:169], v[218:221], v[68:71]
	v_mfma_f32_16x16x32_bf16 v[64:67], v[186:189], v[218:221], v[64:67]
	s_setprio 0
	s_barrier
	s_add_u32 s98, s12, s48
	s_addc_u32 s99, s13, s49
	s_add_i32 s6, s38, s84
	s_mov_b32 m0, s6
	ds_read_b128 v[190:193], v181 offset:49152
	ds_read_b128 v[194:197], v181 offset:50176
	ds_read_b128 v[198:201], v181 offset:51200
	ds_read_b128 v[202:205], v181 offset:52224
	ds_read_b128 v[206:209], v181 offset:53248
	ds_read_b128 v[210:213], v181 offset:54272
	ds_read_b128 v[214:217], v181 offset:55296
	ds_read_b128 v[218:221], v181 offset:56320
	global_load_lds_dwordx4 v146, s[98:99]
	s_add_i32 m0, s6, 0x2000
	s_add_u32 s6, s12, 0x40080
	s_addc_u32 s7, s13, 0
	s_add_i32 s12, s39, s84
	global_load_lds_dwordx4 v150, s[98:99]
	s_mov_b32 m0, s12
	s_nop 0
	global_load_lds_dwordx4 v146, s[6:7]
	s_add_i32 m0, s12, 0x2000
	s_nop 0
	global_load_lds_dwordx4 v150, s[6:7]
	s_mov_b32 m0, s33
	s_nop 0
	global_load_lds_dwordx4 v144, s[10:11]
	s_mov_b32 m0, s56
	s_nop 0
	global_load_lds_dwordx4 v148, s[10:11]
	s_waitcnt vmcnt(8)
	s_waitcnt lgkmcnt(0)
	s_barrier
	s_setprio 1
	s_waitcnt lgkmcnt(0)
	v_mfma_f32_16x16x32_bf16 v[60:63], v[128:131], v[190:193], v[60:63]
	v_mfma_f32_16x16x32_bf16 v[56:59], v[136:139], v[190:193], v[56:59]
	v_mfma_f32_16x16x32_bf16 v[44:47], v[128:131], v[198:201], v[44:47]
	v_mfma_f32_16x16x32_bf16 v[40:43], v[136:139], v[198:201], v[40:43]
	v_mfma_f32_16x16x32_bf16 v[28:31], v[128:131], v[206:209], v[28:31]
	v_mfma_f32_16x16x32_bf16 v[24:27], v[136:139], v[206:209], v[24:27]
	v_mfma_f32_16x16x32_bf16 v[12:15], v[128:131], v[214:217], v[12:15]
	v_mfma_f32_16x16x32_bf16 v[8:11], v[136:139], v[214:217], v[8:11]
	v_mfma_f32_16x16x32_bf16 v[60:63], v[132:135], v[194:197], v[60:63]
	v_mfma_f32_16x16x32_bf16 v[56:59], v[140:143], v[194:197], v[56:59]
	v_mfma_f32_16x16x32_bf16 v[44:47], v[132:135], v[202:205], v[44:47]
	v_mfma_f32_16x16x32_bf16 v[40:43], v[140:143], v[202:205], v[40:43]
	v_mfma_f32_16x16x32_bf16 v[28:31], v[132:135], v[210:213], v[28:31]
	v_mfma_f32_16x16x32_bf16 v[24:27], v[140:143], v[210:213], v[24:27]
	v_mfma_f32_16x16x32_bf16 v[12:15], v[132:135], v[218:221], v[12:15]
	v_mfma_f32_16x16x32_bf16 v[8:11], v[140:143], v[218:221], v[8:11]
	s_setprio 0
	s_setprio 1
	v_mfma_f32_16x16x32_bf16 v[52:55], v[162:165], v[190:193], v[52:55]
	v_mfma_f32_16x16x32_bf16 v[48:51], v[170:173], v[190:193], v[48:51]
	v_mfma_f32_16x16x32_bf16 v[36:39], v[162:165], v[198:201], v[36:39]
	v_mfma_f32_16x16x32_bf16 v[32:35], v[170:173], v[198:201], v[32:35]
	v_mfma_f32_16x16x32_bf16 v[20:23], v[162:165], v[206:209], v[20:23]
	v_mfma_f32_16x16x32_bf16 v[16:19], v[170:173], v[206:209], v[16:19]
	v_mfma_f32_16x16x32_bf16 v[4:7], v[162:165], v[214:217], v[4:7]
	v_mfma_f32_16x16x32_bf16 v[0:3], v[170:173], v[214:217], v[0:3]
	v_mfma_f32_16x16x32_bf16 v[52:55], v[166:169], v[194:197], v[52:55]
	v_mfma_f32_16x16x32_bf16 v[48:51], v[186:189], v[194:197], v[48:51]
	v_mfma_f32_16x16x32_bf16 v[36:39], v[166:169], v[202:205], v[36:39]
	v_mfma_f32_16x16x32_bf16 v[32:35], v[186:189], v[202:205], v[32:35]
	v_mfma_f32_16x16x32_bf16 v[20:23], v[166:169], v[210:213], v[20:23]
	v_mfma_f32_16x16x32_bf16 v[16:19], v[186:189], v[210:213], v[16:19]
	v_mfma_f32_16x16x32_bf16 v[4:7], v[166:169], v[218:221], v[4:7]
	v_mfma_f32_16x16x32_bf16 v[0:3], v[186:189], v[218:221], v[0:3]
	s_setprio 0
	s_barrier
	s_add_i32 s92, s92, 2
	s_add_u32 vcc_lo, vcc_lo, 0x100
	s_addc_u32 vcc_hi, vcc_hi, 0
	s_cmp_gt_u32 s92, 13
	s_mov_b64 s[6:7], s[8:9]
	s_cbranch_scc0 .LBB0_228
	s_and_b64 vcc, exec, s[82:83]
	s_cbranch_vccz .LBB0_231
	s_barrier

.LBB0_448:
	v_add_u32_e32 v1, s78, v210
	ds_read_b128 v[132:135], v1
	ds_read_b128 v[136:139], v1 offset:1024
	ds_read_b128 v[140:143], v1 offset:2048
	ds_read_b128 v[144:147], v1 offset:3072
	v_add_u32_e32 v1, s79, v210
	s_add_u32 s48, s38, s46
	ds_read_b128 v[148:151], v1
	ds_read_b128 v[152:155], v1 offset:1024
	ds_read_b128 v[156:159], v1 offset:2048
	ds_read_b128 v[160:163], v1 offset:3072
	s_addc_u32 s49, s39, s47
	s_add_u32 s48, s48, 0x10000
	s_addc_u32 s49, s49, 0
	s_cmp_eq_u32 s46, 0xf0000
	s_cselect_b32 s64, s81, s48
	s_cselect_b32 s65, s21, s49
	s_cselect_b32 s50, s83, s41
	s_cselect_b32 s51, s19, s86
	s_add_u32 s48, s64, 0x8000
	s_addc_u32 s49, s65, 0
	v_lshl_add_u64 v[2:3], v[204:205], 0, s[46:47]
	s_add_i32 m0, s35, 0xc000
	ds_read_b128 v[164:167], v211
	ds_read_b128 v[168:171], v211 offset:1024
	ds_read_b128 v[172:175], v211 offset:2048
	ds_read_b128 v[176:179], v211 offset:3072
	ds_read_b128 v[180:183], v211 offset:4096
	ds_read_b128 v[184:187], v211 offset:5120
	ds_read_b128 v[212:215], v211 offset:6144
	ds_read_b128 v[216:219], v211 offset:7168
	global_load_lds_dwordx4 v[2:3], off
	v_lshl_add_u64 v[2:3], v[206:207], 0, s[46:47]
	s_add_i32 m0, s35, 0xe000
	s_nop 0
	global_load_lds_dwordx4 v[2:3], off
	s_nop 0
	s_waitcnt vmcnt(8)
	s_waitcnt lgkmcnt(0)
	s_barrier
	s_setprio 1
	s_waitcnt lgkmcnt(0)
	v_mfma_f32_16x16x32_bf16 v[128:131], v[132:135], v[164:167], v[128:131]
	v_mfma_f32_16x16x32_bf16 v[124:127], v[140:143], v[164:167], v[124:127]
	v_mfma_f32_16x16x32_bf16 v[112:115], v[132:135], v[172:175], v[112:115]
	v_mfma_f32_16x16x32_bf16 v[108:111], v[140:143], v[172:175], v[108:111]
	v_mfma_f32_16x16x32_bf16 v[96:99], v[132:135], v[180:183], v[96:99]
	v_mfma_f32_16x16x32_bf16 v[92:95], v[140:143], v[180:183], v[92:95]
	v_mfma_f32_16x16x32_bf16 v[80:83], v[132:135], v[212:215], v[80:83]
	v_mfma_f32_16x16x32_bf16 v[76:79], v[140:143], v[212:215], v[76:79]
	v_mfma_f32_16x16x32_bf16 v[128:131], v[136:139], v[168:171], v[128:131]
	v_mfma_f32_16x16x32_bf16 v[124:127], v[144:147], v[168:171], v[124:127]
	v_mfma_f32_16x16x32_bf16 v[112:115], v[136:139], v[176:179], v[112:115]
	v_mfma_f32_16x16x32_bf16 v[108:111], v[144:147], v[176:179], v[108:111]
	v_mfma_f32_16x16x32_bf16 v[96:99], v[136:139], v[184:187], v[96:99]
	v_mfma_f32_16x16x32_bf16 v[92:95], v[144:147], v[184:187], v[92:95]
	v_mfma_f32_16x16x32_bf16 v[80:83], v[136:139], v[216:219], v[80:83]
	v_mfma_f32_16x16x32_bf16 v[76:79], v[144:147], v[216:219], v[76:79]
	s_setprio 0
	s_setprio 1
	v_mfma_f32_16x16x32_bf16 v[120:123], v[148:151], v[164:167], v[120:123]
	v_mfma_f32_16x16x32_bf16 v[116:119], v[156:159], v[164:167], v[116:119]
	v_mfma_f32_16x16x32_bf16 v[104:107], v[148:151], v[172:175], v[104:107]
	v_mfma_f32_16x16x32_bf16 v[100:103], v[156:159], v[172:175], v[100:103]
	v_mfma_f32_16x16x32_bf16 v[88:91], v[148:151], v[180:183], v[88:91]
	v_mfma_f32_16x16x32_bf16 v[84:87], v[156:159], v[180:183], v[84:87]
	v_mfma_f32_16x16x32_bf16 v[72:75], v[148:151], v[212:215], v[72:75]
	v_mfma_f32_16x16x32_bf16 v[68:71], v[156:159], v[212:215], v[68:71]
	v_mfma_f32_16x16x32_bf16 v[120:123], v[152:155], v[168:171], v[120:123]
	v_mfma_f32_16x16x32_bf16 v[116:119], v[160:163], v[168:171], v[116:119]
	v_mfma_f32_16x16x32_bf16 v[104:107], v[152:155], v[176:179], v[104:107]
	v_mfma_f32_16x16x32_bf16 v[100:103], v[160:163], v[176:179], v[100:103]
	v_mfma_f32_16x16x32_bf16 v[88:91], v[152:155], v[184:187], v[88:91]
	v_mfma_f32_16x16x32_bf16 v[84:87], v[160:163], v[184:187], v[84:87]
	v_mfma_f32_16x16x32_bf16 v[72:75], v[152:155], v[216:219], v[72:75]
	v_mfma_f32_16x16x32_bf16 v[68:71], v[160:163], v[216:219], v[68:71]
	s_setprio 0
	s_barrier
	s_add_i32 s88, s78, s34
	s_mov_b32 m0, s88
	ds_read_b128 v[164:167], v211 offset:16384
	ds_read_b128 v[168:171], v211 offset:17408
	ds_read_b128 v[172:175], v211 offset:18432
	ds_read_b128 v[176:179], v211 offset:19456
	ds_read_b128 v[180:183], v211 offset:20480
	ds_read_b128 v[184:187], v211 offset:21504
	ds_read_b128 v[212:215], v211 offset:22528
	ds_read_b128 v[216:219], v211 offset:23552
	global_load_lds_dwordx4 v192, s[50:51]
	s_add_i32 m0, s88, 0x2000
	s_add_u32 s88, s50, 0x80000
	v_lshl_add_u64 v[222:223], s[50:51], 0, v[188:189]
	s_addc_u32 s89, s51, 0
	s_add_i32 s90, s79, s34
	global_load_lds_dwordx4 v[222:223], off
	s_mov_b32 m0, s90
	s_nop 0
	global_load_lds_dwordx4 v192, s[88:89]
	s_add_i32 m0, s90, 0x2000
	s_nop 0
	global_load_lds_dwordx4 v188, s[88:89]
	s_mov_b32 m0, s35
	s_nop 0
	global_load_lds_dwordx4 v194, s[64:65]
	s_mov_b32 m0, s56
	s_nop 0
	global_load_lds_dwordx4 v190, s[64:65]
	s_waitcnt vmcnt(8)
	s_waitcnt lgkmcnt(0)
	s_barrier
	s_setprio 1
	s_waitcnt lgkmcnt(0)
	v_mfma_f32_16x16x32_bf16 v[64:67], v[132:135], v[164:167], v[64:67]
	v_mfma_f32_16x16x32_bf16 v[60:63], v[140:143], v[164:167], v[60:63]
	v_mfma_f32_16x16x32_bf16 v[48:51], v[132:135], v[172:175], v[48:51]
	v_mfma_f32_16x16x32_bf16 v[44:47], v[140:143], v[172:175], v[44:47]
	v_mfma_f32_16x16x32_bf16 v[32:35], v[132:135], v[180:183], v[32:35]
	v_mfma_f32_16x16x32_bf16 v[28:31], v[140:143], v[180:183], v[28:31]
	v_mfma_f32_16x16x32_bf16 v[16:19], v[132:135], v[212:215], v[16:19]
	v_mfma_f32_16x16x32_bf16 v[12:15], v[140:143], v[212:215], v[12:15]
	v_mfma_f32_16x16x32_bf16 v[64:67], v[136:139], v[168:171], v[64:67]
	v_mfma_f32_16x16x32_bf16 v[60:63], v[144:147], v[168:171], v[60:63]
	v_mfma_f32_16x16x32_bf16 v[48:51], v[136:139], v[176:179], v[48:51]
	v_mfma_f32_16x16x32_bf16 v[44:47], v[144:147], v[176:179], v[44:47]
	v_mfma_f32_16x16x32_bf16 v[32:35], v[136:139], v[184:187], v[32:35]
	v_mfma_f32_16x16x32_bf16 v[28:31], v[144:147], v[184:187], v[28:31]
	v_mfma_f32_16x16x32_bf16 v[16:19], v[136:139], v[216:219], v[16:19]
	v_mfma_f32_16x16x32_bf16 v[12:15], v[144:147], v[216:219], v[12:15]
	s_setprio 0
	s_setprio 1
	v_mfma_f32_16x16x32_bf16 v[56:59], v[148:151], v[164:167], v[56:59]
	v_mfma_f32_16x16x32_bf16 v[52:55], v[156:159], v[164:167], v[52:55]
	v_mfma_f32_16x16x32_bf16 v[40:43], v[148:151], v[172:175], v[40:43]
	v_mfma_f32_16x16x32_bf16 v[36:39], v[156:159], v[172:175], v[36:39]
	v_mfma_f32_16x16x32_bf16 v[24:27], v[148:151], v[180:183], v[24:27]
	v_mfma_f32_16x16x32_bf16 v[20:23], v[156:159], v[180:183], v[20:23]
	v_mfma_f32_16x16x32_bf16 v[8:11], v[148:151], v[212:215], v[8:11]
	v_mfma_f32_16x16x32_bf16 v[2:5], v[156:159], v[212:215], v[4:7]
	v_mfma_f32_16x16x32_bf16 v[56:59], v[152:155], v[168:171], v[56:59]
	v_mfma_f32_16x16x32_bf16 v[52:55], v[160:163], v[168:171], v[52:55]
	v_mfma_f32_16x16x32_bf16 v[40:43], v[152:155], v[176:179], v[40:43]
	v_mfma_f32_16x16x32_bf16 v[36:39], v[160:163], v[176:179], v[36:39]
	v_mfma_f32_16x16x32_bf16 v[24:27], v[152:155], v[184:187], v[24:27]
	v_mfma_f32_16x16x32_bf16 v[20:23], v[160:163], v[184:187], v[20:23]
	v_mfma_f32_16x16x32_bf16 v[8:11], v[152:155], v[216:219], v[8:11]
	v_mfma_f32_16x16x32_bf16 v[2:5], v[160:163], v[216:219], v[2:5]
	s_setprio 0
	s_barrier
	s_add_i32 s88, 0, 0x18000
	v_add_u32_e32 v1, s88, v210
	s_add_i32 s89, 0, 0x1c000
	ds_read_b128 v[132:135], v1
	ds_read_b128 v[136:139], v1 offset:1024
	ds_read_b128 v[140:143], v1 offset:2048
	ds_read_b128 v[144:147], v1 offset:3072
	v_add_u32_e32 v1, s89, v210
	ds_read_b128 v[148:151], v1
	ds_read_b128 v[152:155], v1 offset:1024
	ds_read_b128 v[156:159], v1 offset:2048
	ds_read_b128 v[160:163], v1 offset:3072
	s_add_u32 s64, s64, 0x2000
	s_addc_u32 s65, s65, 0
	s_mov_b32 m0, s57
	ds_read_b128 v[164:167], v211 offset:32768
	ds_read_b128 v[168:171], v211 offset:33792
	ds_read_b128 v[172:175], v211 offset:34816
	ds_read_b128 v[176:179], v211 offset:35840
	ds_read_b128 v[180:183], v211 offset:36864
	ds_read_b128 v[184:187], v211 offset:37888
	ds_read_b128 v[212:215], v211 offset:38912
	ds_read_b128 v[216:219], v211 offset:39936
	global_load_lds_dwordx4 v194, s[64:65]
	s_mov_b32 m0, s59
	s_nop 0
	global_load_lds_dwordx4 v190, s[64:65]
	s_nop 0
	s_waitcnt vmcnt(8)
	s_waitcnt lgkmcnt(0)
	s_barrier
	s_setprio 1
	s_waitcnt lgkmcnt(0)
	v_mfma_f32_16x16x32_bf16 v[128:131], v[132:135], v[164:167], v[128:131]
	v_mfma_f32_16x16x32_bf16 v[124:127], v[140:143], v[164:167], v[124:127]
	v_mfma_f32_16x16x32_bf16 v[112:115], v[132:135], v[172:175], v[112:115]
	v_mfma_f32_16x16x32_bf16 v[108:111], v[140:143], v[172:175], v[108:111]
	v_mfma_f32_16x16x32_bf16 v[96:99], v[132:135], v[180:183], v[96:99]
	v_mfma_f32_16x16x32_bf16 v[92:95], v[140:143], v[180:183], v[92:95]
	v_mfma_f32_16x16x32_bf16 v[80:83], v[132:135], v[212:215], v[80:83]
	v_mfma_f32_16x16x32_bf16 v[76:79], v[140:143], v[212:215], v[76:79]
	v_mfma_f32_16x16x32_bf16 v[128:131], v[136:139], v[168:171], v[128:131]
	v_mfma_f32_16x16x32_bf16 v[124:127], v[144:147], v[168:171], v[124:127]
	v_mfma_f32_16x16x32_bf16 v[112:115], v[136:139], v[176:179], v[112:115]
	v_mfma_f32_16x16x32_bf16 v[108:111], v[144:147], v[176:179], v[108:111]
	v_mfma_f32_16x16x32_bf16 v[96:99], v[136:139], v[184:187], v[96:99]
	v_mfma_f32_16x16x32_bf16 v[92:95], v[144:147], v[184:187], v[92:95]
	v_mfma_f32_16x16x32_bf16 v[80:83], v[136:139], v[216:219], v[80:83]
	v_mfma_f32_16x16x32_bf16 v[76:79], v[144:147], v[216:219], v[76:79]
	s_setprio 0
	s_setprio 1
	v_mfma_f32_16x16x32_bf16 v[120:123], v[148:151], v[164:167], v[120:123]
	v_mfma_f32_16x16x32_bf16 v[116:119], v[156:159], v[164:167], v[116:119]
	v_mfma_f32_16x16x32_bf16 v[104:107], v[148:151], v[172:175], v[104:107]
	v_mfma_f32_16x16x32_bf16 v[100:103], v[156:159], v[172:175], v[100:103]
	v_mfma_f32_16x16x32_bf16 v[88:91], v[148:151], v[180:183], v[88:91]
	v_mfma_f32_16x16x32_bf16 v[84:87], v[156:159], v[180:183], v[84:87]
	v_mfma_f32_16x16x32_bf16 v[72:75], v[148:151], v[212:215], v[72:75]
	v_mfma_f32_16x16x32_bf16 v[68:71], v[156:159], v[212:215], v[68:71]
	v_mfma_f32_16x16x32_bf16 v[120:123], v[152:155], v[168:171], v[120:123]
	v_mfma_f32_16x16x32_bf16 v[116:119], v[160:163], v[168:171], v[116:119]
	v_mfma_f32_16x16x32_bf16 v[104:107], v[152:155], v[176:179], v[104:107]
	v_mfma_f32_16x16x32_bf16 v[100:103], v[160:163], v[176:179], v[100:103]
	v_mfma_f32_16x16x32_bf16 v[88:91], v[152:155], v[184:187], v[88:91]
	v_mfma_f32_16x16x32_bf16 v[84:87], v[160:163], v[184:187], v[84:87]
	v_mfma_f32_16x16x32_bf16 v[72:75], v[152:155], v[216:219], v[72:75]
	v_mfma_f32_16x16x32_bf16 v[68:71], v[160:163], v[216:219], v[68:71]
	s_setprio 0
	s_barrier
	s_add_u32 s98, s50, s10
	s_addc_u32 s99, s51, s11
	s_add_i32 s64, s88, s34
	s_mov_b32 m0, s64
	ds_read_b128 v[164:167], v211 offset:49152
	ds_read_b128 v[168:171], v211 offset:50176
	ds_read_b128 v[172:175], v211 offset:51200
	ds_read_b128 v[176:179], v211 offset:52224
	ds_read_b128 v[180:183], v211 offset:53248
	ds_read_b128 v[184:187], v211 offset:54272
	ds_read_b128 v[212:215], v211 offset:55296
	ds_read_b128 v[216:219], v211 offset:56320
	global_load_lds_dwordx4 v192, s[98:99]
	s_add_i32 m0, s64, 0x2000
	s_add_u32 s50, s50, 0x80080
	v_lshl_add_u64 v[6:7], v[222:223], 0, s[10:11]
	s_addc_u32 s51, s51, 0
	s_add_i32 s64, s89, s34
	global_load_lds_dwordx4 v[6:7], off
	s_mov_b32 m0, s64
	s_nop 0
	global_load_lds_dwordx4 v192, s[50:51]
	s_add_i32 m0, s64, 0x2000
	s_nop 0
	global_load_lds_dwordx4 v188, s[50:51]
	s_mov_b32 m0, s74
	s_nop 0
	global_load_lds_dwordx4 v194, s[48:49]
	s_mov_b32 m0, s75
	s_nop 0
	global_load_lds_dwordx4 v190, s[48:49]
	s_waitcnt vmcnt(8)
	s_waitcnt lgkmcnt(0)
	s_barrier
	s_setprio 1
	s_waitcnt lgkmcnt(0)
	v_mfma_f32_16x16x32_bf16 v[64:67], v[132:135], v[164:167], v[64:67]
	v_mfma_f32_16x16x32_bf16 v[60:63], v[140:143], v[164:167], v[60:63]
	v_mfma_f32_16x16x32_bf16 v[48:51], v[132:135], v[172:175], v[48:51]
	v_mfma_f32_16x16x32_bf16 v[44:47], v[140:143], v[172:175], v[44:47]
	v_mfma_f32_16x16x32_bf16 v[32:35], v[132:135], v[180:183], v[32:35]
	v_mfma_f32_16x16x32_bf16 v[28:31], v[140:143], v[180:183], v[28:31]
	v_mfma_f32_16x16x32_bf16 v[16:19], v[132:135], v[212:215], v[16:19]
	v_mfma_f32_16x16x32_bf16 v[12:15], v[140:143], v[212:215], v[12:15]
	v_mfma_f32_16x16x32_bf16 v[64:67], v[136:139], v[168:171], v[64:67]
	v_mfma_f32_16x16x32_bf16 v[60:63], v[144:147], v[168:171], v[60:63]
	v_mfma_f32_16x16x32_bf16 v[48:51], v[136:139], v[176:179], v[48:51]
	v_mfma_f32_16x16x32_bf16 v[44:47], v[144:147], v[176:179], v[44:47]
	v_mfma_f32_16x16x32_bf16 v[32:35], v[136:139], v[184:187], v[32:35]
	v_mfma_f32_16x16x32_bf16 v[28:31], v[144:147], v[184:187], v[28:31]
	v_mfma_f32_16x16x32_bf16 v[16:19], v[136:139], v[216:219], v[16:19]
	v_mfma_f32_16x16x32_bf16 v[12:15], v[144:147], v[216:219], v[12:15]
	s_setprio 0
	s_setprio 1
	v_mfma_f32_16x16x32_bf16 v[56:59], v[148:151], v[164:167], v[56:59]
	v_mfma_f32_16x16x32_bf16 v[52:55], v[156:159], v[164:167], v[52:55]
	v_mfma_f32_16x16x32_bf16 v[40:43], v[148:151], v[172:175], v[40:43]
	v_mfma_f32_16x16x32_bf16 v[36:39], v[156:159], v[172:175], v[36:39]
	v_mfma_f32_16x16x32_bf16 v[24:27], v[148:151], v[180:183], v[24:27]
	v_mfma_f32_16x16x32_bf16 v[20:23], v[156:159], v[180:183], v[20:23]
	v_mfma_f32_16x16x32_bf16 v[6:9], v[148:151], v[212:215], v[8:11]
	v_mfma_f32_16x16x32_bf16 v[2:5], v[156:159], v[212:215], v[2:5]
	v_mfma_f32_16x16x32_bf16 v[56:59], v[152:155], v[168:171], v[56:59]
	v_mfma_f32_16x16x32_bf16 v[52:55], v[160:163], v[168:171], v[52:55]
	v_mfma_f32_16x16x32_bf16 v[40:43], v[152:155], v[176:179], v[40:43]
	v_mfma_f32_16x16x32_bf16 v[36:39], v[160:163], v[176:179], v[36:39]
	v_mfma_f32_16x16x32_bf16 v[24:27], v[152:155], v[184:187], v[24:27]
	v_mfma_f32_16x16x32_bf16 v[20:23], v[160:163], v[184:187], v[20:23]
	v_mfma_f32_16x16x32_bf16 v[8:11], v[152:155], v[216:219], v[6:9]
	v_mfma_f32_16x16x32_bf16 v[4:7], v[160:163], v[216:219], v[2:5]
	s_setprio 0
	s_barrier
	s_add_i32 s87, s87, 2
	s_add_u32 s41, s41, 0x100
	s_addc_u32 s86, s86, 0
	s_add_u32 s46, s46, 0x10000
	s_addc_u32 s47, s47, 0
	s_cmp_gt_u32 s87, 29
	s_cbranch_scc1 .LBB0_440

.LBB0_507:
	ds_read_b128 v[128:131], v229
	ds_read_b128 v[132:135], v229 offset:1024
	ds_read_b128 v[136:139], v229 offset:2048
	ds_read_b128 v[140:143], v229 offset:3072
	ds_read_b128 v[144:147], v230
	ds_read_b128 v[148:151], v230 offset:1024
	ds_read_b128 v[152:155], v230 offset:2048
	ds_read_b128 v[156:159], v230 offset:3072
	s_add_u32 s44, s42, 0x10000
	s_addc_u32 s45, s43, 0
	s_cmp_eq_u32 s83, 12
	s_cselect_b32 s50, s21, s44
	s_cselect_b32 s51, s8, s45
	s_cselect_b32 s48, s29, s80
	s_cselect_b32 s49, s27, s81
	s_add_u32 s46, s50, 0x8000
	s_addc_u32 s47, s51, 0
	s_add_i32 m0, s23, 0xc000
	ds_read_b128 v[160:163], v231
	ds_read_b128 v[164:167], v231 offset:1024
	ds_read_b128 v[168:171], v231 offset:2048
	ds_read_b128 v[172:175], v231 offset:3072
	ds_read_b128 v[176:179], v231 offset:4096
	ds_read_b128 v[180:183], v231 offset:5120
	ds_read_b128 v[184:187], v231 offset:6144
	ds_read_b128 v[188:191], v231 offset:7168
	global_load_lds_dwordx4 v200, s[42:43]
	s_add_i32 m0, s23, 0xe000
	s_nop 0
	global_load_lds_dwordx4 v202, s[42:43]
	s_waitcnt vmcnt(8)
	s_waitcnt lgkmcnt(0)
	s_barrier
	s_setprio 1
	s_waitcnt lgkmcnt(0)
	v_mfma_f32_16x16x32_bf16 v[124:127], v[128:131], v[160:163], v[124:127]
	v_mfma_f32_16x16x32_bf16 v[120:123], v[136:139], v[160:163], v[120:123]
	v_mfma_f32_16x16x32_bf16 v[108:111], v[128:131], v[168:171], v[108:111]
	v_mfma_f32_16x16x32_bf16 v[104:107], v[136:139], v[168:171], v[104:107]
	v_mfma_f32_16x16x32_bf16 v[92:95], v[128:131], v[176:179], v[92:95]
	v_mfma_f32_16x16x32_bf16 v[88:91], v[136:139], v[176:179], v[88:91]
	v_mfma_f32_16x16x32_bf16 v[76:79], v[128:131], v[184:187], v[76:79]
	v_mfma_f32_16x16x32_bf16 v[72:75], v[136:139], v[184:187], v[72:75]
	v_mfma_f32_16x16x32_bf16 v[124:127], v[132:135], v[164:167], v[124:127]
	v_mfma_f32_16x16x32_bf16 v[120:123], v[140:143], v[164:167], v[120:123]
	v_mfma_f32_16x16x32_bf16 v[108:111], v[132:135], v[172:175], v[108:111]
	v_mfma_f32_16x16x32_bf16 v[104:107], v[140:143], v[172:175], v[104:107]
	v_mfma_f32_16x16x32_bf16 v[92:95], v[132:135], v[180:183], v[92:95]
	v_mfma_f32_16x16x32_bf16 v[88:91], v[140:143], v[180:183], v[88:91]
	v_mfma_f32_16x16x32_bf16 v[76:79], v[132:135], v[188:191], v[76:79]
	v_mfma_f32_16x16x32_bf16 v[72:75], v[140:143], v[188:191], v[72:75]
	s_setprio 0
	s_setprio 1
	v_mfma_f32_16x16x32_bf16 v[116:119], v[144:147], v[160:163], v[116:119]
	v_mfma_f32_16x16x32_bf16 v[112:115], v[152:155], v[160:163], v[112:115]
	v_mfma_f32_16x16x32_bf16 v[100:103], v[144:147], v[168:171], v[100:103]
	v_mfma_f32_16x16x32_bf16 v[96:99], v[152:155], v[168:171], v[96:99]
	v_mfma_f32_16x16x32_bf16 v[84:87], v[144:147], v[176:179], v[84:87]
	v_mfma_f32_16x16x32_bf16 v[80:83], v[152:155], v[176:179], v[80:83]
	v_mfma_f32_16x16x32_bf16 v[68:71], v[144:147], v[184:187], v[68:71]
	v_mfma_f32_16x16x32_bf16 v[64:67], v[152:155], v[184:187], v[64:67]
	v_mfma_f32_16x16x32_bf16 v[116:119], v[148:151], v[164:167], v[116:119]
	v_mfma_f32_16x16x32_bf16 v[112:115], v[156:159], v[164:167], v[112:115]
	v_mfma_f32_16x16x32_bf16 v[100:103], v[148:151], v[172:175], v[100:103]
	v_mfma_f32_16x16x32_bf16 v[96:99], v[156:159], v[172:175], v[96:99]
	v_mfma_f32_16x16x32_bf16 v[84:87], v[148:151], v[180:183], v[84:87]
	v_mfma_f32_16x16x32_bf16 v[80:83], v[156:159], v[180:183], v[80:83]
	v_mfma_f32_16x16x32_bf16 v[68:71], v[148:151], v[188:191], v[68:71]
	v_mfma_f32_16x16x32_bf16 v[64:67], v[156:159], v[188:191], v[64:67]
	s_setprio 0
	s_barrier
	s_add_i32 s42, s77, s35
	s_mov_b32 m0, s42
	ds_read_b128 v[160:163], v231 offset:16384
	ds_read_b128 v[164:167], v231 offset:17408
	ds_read_b128 v[168:171], v231 offset:18432
	ds_read_b128 v[172:175], v231 offset:19456
	ds_read_b128 v[176:179], v231 offset:20480
	ds_read_b128 v[180:183], v231 offset:21504
	ds_read_b128 v[184:187], v231 offset:22528
	ds_read_b128 v[188:191], v231 offset:23552
	global_load_lds_dwordx4 v194, s[48:49]
	s_add_i32 m0, s42, 0x2000
	s_add_u32 s42, s48, 0x40000
	s_addc_u32 s43, s49, 0
	s_add_i32 s84, s78, s35
	global_load_lds_dwordx4 v198, s[48:49]
	s_mov_b32 m0, s84
	s_nop 0
	global_load_lds_dwordx4 v194, s[42:43]
	s_add_i32 m0, s84, 0x2000
	s_nop 0
	global_load_lds_dwordx4 v198, s[42:43]
	s_mov_b32 m0, s23
	s_nop 0
	global_load_lds_dwordx4 v192, s[50:51]
	s_mov_b32 m0, s56
	s_nop 0
	global_load_lds_dwordx4 v196, s[50:51]
	s_waitcnt vmcnt(8)
	s_waitcnt lgkmcnt(0)
	s_barrier
	s_setprio 1
	s_waitcnt lgkmcnt(0)
	v_mfma_f32_16x16x32_bf16 v[60:63], v[128:131], v[160:163], v[60:63]
	v_mfma_f32_16x16x32_bf16 v[56:59], v[136:139], v[160:163], v[56:59]
	v_mfma_f32_16x16x32_bf16 v[44:47], v[128:131], v[168:171], v[44:47]
	v_mfma_f32_16x16x32_bf16 v[40:43], v[136:139], v[168:171], v[40:43]
	v_mfma_f32_16x16x32_bf16 v[28:31], v[128:131], v[176:179], v[28:31]
	v_mfma_f32_16x16x32_bf16 v[24:27], v[136:139], v[176:179], v[24:27]
	v_mfma_f32_16x16x32_bf16 v[12:15], v[128:131], v[184:187], v[12:15]
	v_mfma_f32_16x16x32_bf16 v[8:11], v[136:139], v[184:187], v[8:11]
	v_mfma_f32_16x16x32_bf16 v[60:63], v[132:135], v[164:167], v[60:63]
	v_mfma_f32_16x16x32_bf16 v[56:59], v[140:143], v[164:167], v[56:59]
	v_mfma_f32_16x16x32_bf16 v[44:47], v[132:135], v[172:175], v[44:47]
	v_mfma_f32_16x16x32_bf16 v[40:43], v[140:143], v[172:175], v[40:43]
	v_mfma_f32_16x16x32_bf16 v[28:31], v[132:135], v[180:183], v[28:31]
	v_mfma_f32_16x16x32_bf16 v[24:27], v[140:143], v[180:183], v[24:27]
	v_mfma_f32_16x16x32_bf16 v[12:15], v[132:135], v[188:191], v[12:15]
	v_mfma_f32_16x16x32_bf16 v[8:11], v[140:143], v[188:191], v[8:11]
	s_setprio 0
	s_setprio 1
	v_mfma_f32_16x16x32_bf16 v[52:55], v[144:147], v[160:163], v[52:55]
	v_mfma_f32_16x16x32_bf16 v[48:51], v[152:155], v[160:163], v[48:51]
	v_mfma_f32_16x16x32_bf16 v[36:39], v[144:147], v[168:171], v[36:39]
	v_mfma_f32_16x16x32_bf16 v[32:35], v[152:155], v[168:171], v[32:35]
	v_mfma_f32_16x16x32_bf16 v[20:23], v[144:147], v[176:179], v[20:23]
	v_mfma_f32_16x16x32_bf16 v[16:19], v[152:155], v[176:179], v[16:19]
	v_mfma_f32_16x16x32_bf16 v[4:7], v[144:147], v[184:187], v[4:7]
	v_mfma_f32_16x16x32_bf16 v[0:3], v[152:155], v[184:187], v[0:3]
	v_mfma_f32_16x16x32_bf16 v[52:55], v[148:151], v[164:167], v[52:55]
	v_mfma_f32_16x16x32_bf16 v[48:51], v[156:159], v[164:167], v[48:51]
	v_mfma_f32_16x16x32_bf16 v[36:39], v[148:151], v[172:175], v[36:39]
	v_mfma_f32_16x16x32_bf16 v[32:35], v[156:159], v[172:175], v[32:35]
	v_mfma_f32_16x16x32_bf16 v[20:23], v[148:151], v[180:183], v[20:23]
	v_mfma_f32_16x16x32_bf16 v[16:19], v[156:159], v[180:183], v[16:19]
	v_mfma_f32_16x16x32_bf16 v[4:7], v[148:151], v[188:191], v[4:7]
	v_mfma_f32_16x16x32_bf16 v[0:3], v[156:159], v[188:191], v[0:3]
	s_setprio 0
	s_barrier
	s_add_i32 s84, 0, 0x18000
	s_add_i32 s85, 0, 0x1c000
	v_add_u32_e32 v140, s84, v228
	v_add_u32_e32 v156, s85, v228
	ds_read_b128 v[128:131], v140
	ds_read_b128 v[132:135], v140 offset:1024
	ds_read_b128 v[136:139], v140 offset:2048
	ds_read_b128 v[140:143], v140 offset:3072
	ds_read_b128 v[144:147], v156
	ds_read_b128 v[148:151], v156 offset:1024
	ds_read_b128 v[152:155], v156 offset:2048
	ds_read_b128 v[156:159], v156 offset:3072
	s_add_u32 s42, s50, 0x2000
	s_addc_u32 s43, s51, 0
	s_mov_b32 m0, s57
	ds_read_b128 v[160:163], v231 offset:32768
	ds_read_b128 v[164:167], v231 offset:33792
	ds_read_b128 v[168:171], v231 offset:34816
	ds_read_b128 v[172:175], v231 offset:35840
	ds_read_b128 v[176:179], v231 offset:36864
	ds_read_b128 v[180:183], v231 offset:37888
	ds_read_b128 v[184:187], v231 offset:38912
	ds_read_b128 v[188:191], v231 offset:39936
	global_load_lds_dwordx4 v192, s[42:43]
	s_mov_b32 m0, s59
	s_nop 0
	global_load_lds_dwordx4 v196, s[42:43]
	s_nop 0
	s_waitcnt vmcnt(8)
	s_waitcnt lgkmcnt(0)
	s_barrier
	s_setprio 1
	s_waitcnt lgkmcnt(0)
	v_mfma_f32_16x16x32_bf16 v[124:127], v[128:131], v[160:163], v[124:127]
	v_mfma_f32_16x16x32_bf16 v[120:123], v[136:139], v[160:163], v[120:123]
	v_mfma_f32_16x16x32_bf16 v[108:111], v[128:131], v[168:171], v[108:111]
	v_mfma_f32_16x16x32_bf16 v[104:107], v[136:139], v[168:171], v[104:107]
	v_mfma_f32_16x16x32_bf16 v[92:95], v[128:131], v[176:179], v[92:95]
	v_mfma_f32_16x16x32_bf16 v[88:91], v[136:139], v[176:179], v[88:91]
	v_mfma_f32_16x16x32_bf16 v[76:79], v[128:131], v[184:187], v[76:79]
	v_mfma_f32_16x16x32_bf16 v[72:75], v[136:139], v[184:187], v[72:75]
	v_mfma_f32_16x16x32_bf16 v[124:127], v[132:135], v[164:167], v[124:127]
	v_mfma_f32_16x16x32_bf16 v[120:123], v[140:143], v[164:167], v[120:123]
	v_mfma_f32_16x16x32_bf16 v[108:111], v[132:135], v[172:175], v[108:111]
	v_mfma_f32_16x16x32_bf16 v[104:107], v[140:143], v[172:175], v[104:107]
	v_mfma_f32_16x16x32_bf16 v[92:95], v[132:135], v[180:183], v[92:95]
	v_mfma_f32_16x16x32_bf16 v[88:91], v[140:143], v[180:183], v[88:91]
	v_mfma_f32_16x16x32_bf16 v[76:79], v[132:135], v[188:191], v[76:79]
	v_mfma_f32_16x16x32_bf16 v[72:75], v[140:143], v[188:191], v[72:75]
	s_setprio 0
	s_setprio 1
	v_mfma_f32_16x16x32_bf16 v[116:119], v[144:147], v[160:163], v[116:119]
	v_mfma_f32_16x16x32_bf16 v[112:115], v[152:155], v[160:163], v[112:115]
	v_mfma_f32_16x16x32_bf16 v[100:103], v[144:147], v[168:171], v[100:103]
	v_mfma_f32_16x16x32_bf16 v[96:99], v[152:155], v[168:171], v[96:99]
	v_mfma_f32_16x16x32_bf16 v[84:87], v[144:147], v[176:179], v[84:87]
	v_mfma_f32_16x16x32_bf16 v[80:83], v[152:155], v[176:179], v[80:83]
	v_mfma_f32_16x16x32_bf16 v[68:71], v[144:147], v[184:187], v[68:71]
	v_mfma_f32_16x16x32_bf16 v[64:67], v[152:155], v[184:187], v[64:67]
	v_mfma_f32_16x16x32_bf16 v[116:119], v[148:151], v[164:167], v[116:119]
	v_mfma_f32_16x16x32_bf16 v[112:115], v[156:159], v[164:167], v[112:115]
	v_mfma_f32_16x16x32_bf16 v[100:103], v[148:151], v[172:175], v[100:103]
	v_mfma_f32_16x16x32_bf16 v[96:99], v[156:159], v[172:175], v[96:99]
	v_mfma_f32_16x16x32_bf16 v[84:87], v[148:151], v[180:183], v[84:87]
	v_mfma_f32_16x16x32_bf16 v[80:83], v[156:159], v[180:183], v[80:83]
	v_mfma_f32_16x16x32_bf16 v[68:71], v[148:151], v[188:191], v[68:71]
	v_mfma_f32_16x16x32_bf16 v[64:67], v[156:159], v[188:191], v[64:67]
	s_setprio 0
	s_barrier
	s_add_u32 s98, s48, s16
	s_addc_u32 s99, s49, s17
	s_add_i32 s42, s84, s35
	s_mov_b32 m0, s42
	ds_read_b128 v[160:163], v231 offset:49152
	ds_read_b128 v[164:167], v231 offset:50176
	ds_read_b128 v[168:171], v231 offset:51200
	ds_read_b128 v[172:175], v231 offset:52224
	ds_read_b128 v[176:179], v231 offset:53248
	ds_read_b128 v[180:183], v231 offset:54272
	ds_read_b128 v[184:187], v231 offset:55296
	ds_read_b128 v[188:191], v231 offset:56320
	global_load_lds_dwordx4 v194, s[98:99]
	s_add_i32 m0, s42, 0x2000
	s_add_u32 s42, s48, 0x40080
	s_addc_u32 s43, s49, 0
	s_add_i32 s48, s85, s35
	global_load_lds_dwordx4 v198, s[98:99]
	s_mov_b32 m0, s48
	s_nop 0
	global_load_lds_dwordx4 v194, s[42:43]
	s_add_i32 m0, s48, 0x2000
	s_nop 0
	global_load_lds_dwordx4 v198, s[42:43]
	s_mov_b32 m0, s75
	s_nop 0
	global_load_lds_dwordx4 v192, s[46:47]
	s_mov_b32 m0, s76
	s_nop 0
	global_load_lds_dwordx4 v196, s[46:47]
	s_waitcnt vmcnt(8)
	s_waitcnt lgkmcnt(0)
	s_barrier
	s_setprio 1
	s_waitcnt lgkmcnt(0)
	v_mfma_f32_16x16x32_bf16 v[60:63], v[128:131], v[160:163], v[60:63]
	v_mfma_f32_16x16x32_bf16 v[56:59], v[136:139], v[160:163], v[56:59]
	v_mfma_f32_16x16x32_bf16 v[44:47], v[128:131], v[168:171], v[44:47]
	v_mfma_f32_16x16x32_bf16 v[40:43], v[136:139], v[168:171], v[40:43]
	v_mfma_f32_16x16x32_bf16 v[28:31], v[128:131], v[176:179], v[28:31]
	v_mfma_f32_16x16x32_bf16 v[24:27], v[136:139], v[176:179], v[24:27]
	v_mfma_f32_16x16x32_bf16 v[12:15], v[128:131], v[184:187], v[12:15]
	v_mfma_f32_16x16x32_bf16 v[8:11], v[136:139], v[184:187], v[8:11]
	v_mfma_f32_16x16x32_bf16 v[60:63], v[132:135], v[164:167], v[60:63]
	v_mfma_f32_16x16x32_bf16 v[56:59], v[140:143], v[164:167], v[56:59]
	v_mfma_f32_16x16x32_bf16 v[44:47], v[132:135], v[172:175], v[44:47]
	v_mfma_f32_16x16x32_bf16 v[40:43], v[140:143], v[172:175], v[40:43]
	v_mfma_f32_16x16x32_bf16 v[28:31], v[132:135], v[180:183], v[28:31]
	v_mfma_f32_16x16x32_bf16 v[24:27], v[140:143], v[180:183], v[24:27]
	v_mfma_f32_16x16x32_bf16 v[12:15], v[132:135], v[188:191], v[12:15]
	v_mfma_f32_16x16x32_bf16 v[8:11], v[140:143], v[188:191], v[8:11]
	s_setprio 0
	s_setprio 1
	v_mfma_f32_16x16x32_bf16 v[52:55], v[144:147], v[160:163], v[52:55]
	v_mfma_f32_16x16x32_bf16 v[48:51], v[152:155], v[160:163], v[48:51]
	v_mfma_f32_16x16x32_bf16 v[36:39], v[144:147], v[168:171], v[36:39]
	v_mfma_f32_16x16x32_bf16 v[32:35], v[152:155], v[168:171], v[32:35]
	v_mfma_f32_16x16x32_bf16 v[20:23], v[144:147], v[176:179], v[20:23]
	v_mfma_f32_16x16x32_bf16 v[16:19], v[152:155], v[176:179], v[16:19]
	v_mfma_f32_16x16x32_bf16 v[4:7], v[144:147], v[184:187], v[4:7]
	v_mfma_f32_16x16x32_bf16 v[0:3], v[152:155], v[184:187], v[0:3]
	v_mfma_f32_16x16x32_bf16 v[52:55], v[148:151], v[164:167], v[52:55]
	v_mfma_f32_16x16x32_bf16 v[48:51], v[156:159], v[164:167], v[48:51]
	v_mfma_f32_16x16x32_bf16 v[36:39], v[148:151], v[172:175], v[36:39]
	v_mfma_f32_16x16x32_bf16 v[32:35], v[156:159], v[172:175], v[32:35]
	v_mfma_f32_16x16x32_bf16 v[20:23], v[148:151], v[180:183], v[20:23]
	v_mfma_f32_16x16x32_bf16 v[16:19], v[156:159], v[180:183], v[16:19]
	v_mfma_f32_16x16x32_bf16 v[4:7], v[148:151], v[188:191], v[4:7]
	v_mfma_f32_16x16x32_bf16 v[0:3], v[156:159], v[188:191], v[0:3]
	s_setprio 0
	s_barrier
	s_add_i32 s83, s83, 2
	s_add_u32 s80, s80, 0x100
	s_addc_u32 s81, s81, 0
	s_cmp_gt_u32 s83, 13
	s_mov_b64 s[42:43], s[44:45]
	s_cbranch_scc0 .LBB0_507
	v_mov_b32_e32 v233, v227
	v_mov_b32_e32 v144, v226
	s_lshl_b32 s8, s22, 8
	s_or_b32 s8, s8, s73
	v_lshlrev_b32_e32 v208, 3, v233
	v_add_u32_e32 v128, s8, v208
	s_lshr_b32 s8, s20, 4
	s_mul_i32 s42, s8, 0x1800
	s_ashr_i32 s43, s42, 31
	s_lshl_b64 s[42:43], s[42:43], 2
	s_add_u32 s42, s69, s42
	v_ashrrev_i32_e32 v129, 31, v128
	v_add_u32_e32 v210, s72, v144
	s_addc_u32 s43, s70, s43
	v_lshlrev_b64 v[212:213], 2, v[128:129]
	v_lshl_add_u32 v216, s20, 8, v210
	v_lshl_add_u64 v[214:215], s[42:43], 0, v[212:213]
	v_ashrrev_i32_e32 v217, 31, v216
	v_add_co_u32_e32 v128, vcc, s65, v214
	v_lshl_add_u64 v[218:219], s[36:37], 0, v[212:213]
	v_lshlrev_b64 v[144:145], 12, v[216:217]
	v_add_u32_e32 v224, 16, v216
	v_lshl_add_u64 v[132:133], v[214:215], 0, s[10:11]
	v_addc_co_u32_e32 v129, vcc, 0, v215, vcc
	v_lshl_add_u64 v[144:145], v[218:219], 0, v[144:145]
	v_ashrrev_i32_e32 v225, 31, v224
	global_load_dwordx4 v[140:143], v[128:129], off nt
	s_nop 0
	global_load_dwordx4 v[128:131], v[132:133], off offset:528 nt
	global_load_dwordx4 v[136:139], v[132:133], off offset:16 nt
	s_nop 0
	global_load_dwordx4 v[132:135], v[132:133], off offset:512 nt
	s_nop 0
	global_load_dwordx4 v[234:237], v[144:145], off offset:16 nt
	global_load_dwordx4 v[238:241], v[144:145], off nt
	global_load_dwordx4 v[242:245], v[144:145], off offset:528 nt
	global_load_dwordx4 v[246:249], v[144:145], off offset:512 nt
	v_lshlrev_b64 v[144:145], 12, v[224:225]
	v_add_u32_e32 v222, 32, v216
	v_lshl_add_u64 v[144:145], v[218:219], 0, v[144:145]
	v_ashrrev_i32_e32 v223, 31, v222
	global_load_dwordx4 v[184:187], v[144:145], off offset:16 nt
	global_load_dwordx4 v[188:191], v[144:145], off nt
	global_load_dwordx4 v[176:179], v[144:145], off offset:528 nt
	global_load_dwordx4 v[180:183], v[144:145], off offset:512 nt
	v_lshlrev_b64 v[144:145], 12, v[222:223]
	v_add_u32_e32 v220, 48, v216
	v_lshl_add_u64 v[144:145], v[218:219], 0, v[144:145]
	v_ashrrev_i32_e32 v221, 31, v220
	global_load_dwordx4 v[168:171], v[144:145], off offset:16 nt
	global_load_dwordx4 v[172:175], v[144:145], off nt
	global_load_dwordx4 v[160:163], v[144:145], off offset:528 nt
	global_load_dwordx4 v[164:167], v[144:145], off offset:512 nt
	v_lshlrev_b64 v[144:145], 12, v[220:221]
	v_lshl_add_u64 v[148:149], v[218:219], 0, v[144:145]
	global_load_dwordx4 v[152:155], v[148:149], off offset:16 nt
	global_load_dwordx4 v[156:159], v[148:149], off nt
	global_load_dwordx4 v[144:147], v[148:149], off offset:528 nt
	s_nop 0
	global_load_dwordx4 v[148:151], v[148:149], off offset:512 nt
	v_and_b32_e32 v211, 64, v232
	v_xor_b32_e32 v209, 16, v232
	v_add_u32_e32 v211, 64, v211
	v_cmp_lt_i32_e32 vcc, v209, v211
	v_xor_b32_e32 v250, 32, v232
	s_lshl_b32 s42, s22, 2
	v_cndmask_b32_e32 v209, v232, v209, vcc
	v_cmp_lt_i32_e32 vcc, v250, v211
	v_lshlrev_b32_e32 v209, 2, v209
	s_ashr_i32 s43, s42, 31
	v_cndmask_b32_e32 v211, v232, v250, vcc
	v_lshlrev_b32_e32 v211, 2, v211
	v_cmp_eq_u32_e32 vcc, 0, v233
	s_waitcnt vmcnt(0)
	v_pk_fma_f32 v[126:127], v[126:127], v[142:143], v[240:241]
	v_pk_fma_f32 v[124:125], v[124:125], v[140:141], v[238:239]
	v_pk_fma_f32 v[120:121], v[120:121], v[136:137], v[234:235]
	v_mul_f32_e32 v233, v125, v125
	v_mul_f32_e32 v234, v127, v127
	v_fmac_f32_e32 v233, v124, v124
	v_fmac_f32_e32 v234, v126, v126
	v_add_f32_e32 v233, v233, v234
	v_mul_f32_e32 v234, v121, v121
	v_pk_fma_f32 v[122:123], v[122:123], v[138:139], v[236:237]
	v_fmac_f32_e32 v234, v120, v120
	v_add_f32_e32 v233, v233, v234
	v_mul_f32_e32 v234, v123, v123
	v_fmac_f32_e32 v234, v122, v122
	v_pk_fma_f32 v[118:119], v[118:119], v[134:135], v[248:249]
	v_pk_fma_f32 v[116:117], v[116:117], v[132:133], v[246:247]
	v_add_f32_e32 v233, v234, v233
	v_mul_f32_e32 v234, v117, v117
	v_mul_f32_e32 v235, v119, v119
	v_pk_fma_f32 v[112:113], v[112:113], v[128:129], v[242:243]
	v_fmac_f32_e32 v234, v116, v116
	v_fmac_f32_e32 v235, v118, v118
	v_add_f32_e32 v234, v234, v235
	v_mul_f32_e32 v235, v113, v113
	v_pk_fma_f32 v[114:115], v[114:115], v[130:131], v[244:245]
	v_fmac_f32_e32 v235, v112, v112
	v_add_f32_e32 v234, v234, v235
	v_mul_f32_e32 v235, v115, v115
	v_fmac_f32_e32 v235, v114, v114
	v_add_f32_e32 v234, v235, v234
	v_add_f32_e32 v233, v233, v234
	ds_bpermute_b32 v234, v209, v233
	s_waitcnt lgkmcnt(0)
	v_add_f32_e32 v233, v233, v234
	ds_bpermute_b32 v234, v211, v233
	s_and_saveexec_b64 s[44:45], vcc
	s_cbranch_execz .LBB0_510
	v_lshlrev_b64 v[236:237], 6, v[216:217]
	v_lshl_add_u64 v[236:237], s[12:13], 0, v[236:237]
	v_lshl_add_u64 v[236:237], s[42:43], 2, v[236:237]
	s_lshl_b32 s8, s71, 2
	v_lshl_add_u64 v[236:237], v[236:237], 0, s[8:9]
	s_waitcnt lgkmcnt(0)
	v_add_f32_e32 v217, v233, v234
	global_store_dword v[236:237], v217, off

.LBB0_568:
	ds_read_b128 v[128:131], v167
	ds_read_b128 v[132:135], v167 offset:1024
	ds_read_b128 v[136:139], v167 offset:2048
	ds_read_b128 v[140:143], v167 offset:3072
	ds_read_b128 v[160:163], v168
	ds_read_b128 v[170:173], v168 offset:1024
	ds_read_b128 v[174:177], v168 offset:2048
	ds_read_b128 v[178:181], v168 offset:3072
	s_add_u32 s36, s28, 0x10000
	s_addc_u32 s37, s29, 0
	s_cmp_eq_u32 s76, 12
	s_cselect_b32 s42, s27, s36
	s_cselect_b32 s43, s19, s37
	s_cselect_b32 s40, s73, s74
	s_cselect_b32 s41, s17, s75
	s_add_u32 s38, s42, 0x8000
	s_addc_u32 s39, s43, 0
	s_add_i32 m0, s44, 0xc000
	ds_read_b128 v[182:185], v169
	ds_read_b128 v[186:189], v169 offset:1024
	ds_read_b128 v[190:193], v169 offset:2048
	ds_read_b128 v[194:197], v169 offset:3072
	ds_read_b128 v[198:201], v169 offset:4096
	ds_read_b128 v[202:205], v169 offset:5120
	ds_read_b128 v[206:209], v169 offset:6144
	ds_read_b128 v[210:213], v169 offset:7168
	global_load_lds_dwordx4 v152, s[28:29]
	s_add_i32 m0, s44, 0xe000
	s_nop 0
	global_load_lds_dwordx4 v154, s[28:29]
	s_nop 0
	s_waitcnt vmcnt(8)
	s_waitcnt lgkmcnt(0)
	s_barrier
	s_setprio 1
	s_waitcnt lgkmcnt(0)
	v_mfma_f32_16x16x32_bf16 v[124:127], v[128:131], v[182:185], v[124:127]
	v_mfma_f32_16x16x32_bf16 v[120:123], v[136:139], v[182:185], v[120:123]
	v_mfma_f32_16x16x32_bf16 v[116:119], v[128:131], v[190:193], v[116:119]
	v_mfma_f32_16x16x32_bf16 v[112:115], v[136:139], v[190:193], v[112:115]
	v_mfma_f32_16x16x32_bf16 v[92:95], v[128:131], v[198:201], v[92:95]
	v_mfma_f32_16x16x32_bf16 v[88:91], v[136:139], v[198:201], v[88:91]
	v_mfma_f32_16x16x32_bf16 v[76:79], v[128:131], v[206:209], v[76:79]
	v_mfma_f32_16x16x32_bf16 v[72:75], v[136:139], v[206:209], v[72:75]
	v_mfma_f32_16x16x32_bf16 v[124:127], v[132:135], v[186:189], v[124:127]
	v_mfma_f32_16x16x32_bf16 v[120:123], v[140:143], v[186:189], v[120:123]
	v_mfma_f32_16x16x32_bf16 v[116:119], v[132:135], v[194:197], v[116:119]
	v_mfma_f32_16x16x32_bf16 v[112:115], v[140:143], v[194:197], v[112:115]
	v_mfma_f32_16x16x32_bf16 v[92:95], v[132:135], v[202:205], v[92:95]
	v_mfma_f32_16x16x32_bf16 v[88:91], v[140:143], v[202:205], v[88:91]
	v_mfma_f32_16x16x32_bf16 v[76:79], v[132:135], v[210:213], v[76:79]
	v_mfma_f32_16x16x32_bf16 v[72:75], v[140:143], v[210:213], v[72:75]
	s_setprio 0
	s_setprio 1
	v_mfma_f32_16x16x32_bf16 v[108:111], v[160:163], v[182:185], v[108:111]
	v_mfma_f32_16x16x32_bf16 v[104:107], v[174:177], v[182:185], v[104:107]
	v_mfma_f32_16x16x32_bf16 v[100:103], v[160:163], v[190:193], v[100:103]
	v_mfma_f32_16x16x32_bf16 v[96:99], v[174:177], v[190:193], v[96:99]
	v_mfma_f32_16x16x32_bf16 v[84:87], v[160:163], v[198:201], v[84:87]
	v_mfma_f32_16x16x32_bf16 v[80:83], v[174:177], v[198:201], v[80:83]
	v_mfma_f32_16x16x32_bf16 v[68:71], v[160:163], v[206:209], v[68:71]
	v_mfma_f32_16x16x32_bf16 v[64:67], v[174:177], v[206:209], v[64:67]
	v_mfma_f32_16x16x32_bf16 v[108:111], v[170:173], v[186:189], v[108:111]
	v_mfma_f32_16x16x32_bf16 v[104:107], v[178:181], v[186:189], v[104:107]
	v_mfma_f32_16x16x32_bf16 v[100:103], v[170:173], v[194:197], v[100:103]
	v_mfma_f32_16x16x32_bf16 v[96:99], v[178:181], v[194:197], v[96:99]
	v_mfma_f32_16x16x32_bf16 v[84:87], v[170:173], v[202:205], v[84:87]
	v_mfma_f32_16x16x32_bf16 v[80:83], v[178:181], v[202:205], v[80:83]
	v_mfma_f32_16x16x32_bf16 v[68:71], v[170:173], v[210:213], v[68:71]
	v_mfma_f32_16x16x32_bf16 v[64:67], v[178:181], v[210:213], v[64:67]
	s_setprio 0
	s_barrier
	s_add_i32 s28, s70, s35
	s_mov_b32 m0, s28
	ds_read_b128 v[182:185], v169 offset:16384
	ds_read_b128 v[186:189], v169 offset:17408
	ds_read_b128 v[190:193], v169 offset:18432
	ds_read_b128 v[194:197], v169 offset:19456
	ds_read_b128 v[198:201], v169 offset:20480
	ds_read_b128 v[202:205], v169 offset:21504
	ds_read_b128 v[206:209], v169 offset:22528
	ds_read_b128 v[210:213], v169 offset:23552
	global_load_lds_dwordx4 v148, s[40:41]
	s_add_i32 m0, s28, 0x2000
	s_add_u32 s28, s40, 0x40000
	s_addc_u32 s29, s41, 0
	s_add_i32 s77, s71, s35
	global_load_lds_dwordx4 v144, s[40:41]
	s_mov_b32 m0, s77
	s_nop 0
	global_load_lds_dwordx4 v148, s[28:29]
	s_add_i32 m0, s77, 0x2000
	s_nop 0
	global_load_lds_dwordx4 v144, s[28:29]
	s_mov_b32 m0, s44
	s_nop 0
	global_load_lds_dwordx4 v150, s[42:43]
	s_mov_b32 m0, s45
	s_nop 0
	global_load_lds_dwordx4 v146, s[42:43]
	s_waitcnt vmcnt(8)
	s_waitcnt lgkmcnt(0)
	s_barrier
	s_setprio 1
	s_waitcnt lgkmcnt(0)
	v_mfma_f32_16x16x32_bf16 v[60:63], v[128:131], v[182:185], v[60:63]
	v_mfma_f32_16x16x32_bf16 v[56:59], v[136:139], v[182:185], v[56:59]
	v_mfma_f32_16x16x32_bf16 v[44:47], v[128:131], v[190:193], v[44:47]
	v_mfma_f32_16x16x32_bf16 v[40:43], v[136:139], v[190:193], v[40:43]
	v_mfma_f32_16x16x32_bf16 v[28:31], v[128:131], v[198:201], v[28:31]
	v_mfma_f32_16x16x32_bf16 v[24:27], v[136:139], v[198:201], v[24:27]
	v_mfma_f32_16x16x32_bf16 v[12:15], v[128:131], v[206:209], v[12:15]
	v_mfma_f32_16x16x32_bf16 v[8:11], v[136:139], v[206:209], v[8:11]
	v_mfma_f32_16x16x32_bf16 v[60:63], v[132:135], v[186:189], v[60:63]
	v_mfma_f32_16x16x32_bf16 v[56:59], v[140:143], v[186:189], v[56:59]
	v_mfma_f32_16x16x32_bf16 v[44:47], v[132:135], v[194:197], v[44:47]
	v_mfma_f32_16x16x32_bf16 v[40:43], v[140:143], v[194:197], v[40:43]
	v_mfma_f32_16x16x32_bf16 v[28:31], v[132:135], v[202:205], v[28:31]
	v_mfma_f32_16x16x32_bf16 v[24:27], v[140:143], v[202:205], v[24:27]
	v_mfma_f32_16x16x32_bf16 v[12:15], v[132:135], v[210:213], v[12:15]
	v_mfma_f32_16x16x32_bf16 v[8:11], v[140:143], v[210:213], v[8:11]
	s_setprio 0
	s_setprio 1
	v_mfma_f32_16x16x32_bf16 v[52:55], v[160:163], v[182:185], v[52:55]
	v_mfma_f32_16x16x32_bf16 v[48:51], v[174:177], v[182:185], v[48:51]
	v_mfma_f32_16x16x32_bf16 v[36:39], v[160:163], v[190:193], v[36:39]
	v_mfma_f32_16x16x32_bf16 v[32:35], v[174:177], v[190:193], v[32:35]
	v_mfma_f32_16x16x32_bf16 v[20:23], v[160:163], v[198:201], v[20:23]
	v_mfma_f32_16x16x32_bf16 v[16:19], v[174:177], v[198:201], v[16:19]
	v_mfma_f32_16x16x32_bf16 v[4:7], v[160:163], v[206:209], v[4:7]
	v_mfma_f32_16x16x32_bf16 v[0:3], v[174:177], v[206:209], v[0:3]
	v_mfma_f32_16x16x32_bf16 v[52:55], v[170:173], v[186:189], v[52:55]
	v_mfma_f32_16x16x32_bf16 v[48:51], v[178:181], v[186:189], v[48:51]
	v_mfma_f32_16x16x32_bf16 v[36:39], v[170:173], v[194:197], v[36:39]
	v_mfma_f32_16x16x32_bf16 v[32:35], v[178:181], v[194:197], v[32:35]
	v_mfma_f32_16x16x32_bf16 v[20:23], v[170:173], v[202:205], v[20:23]
	v_mfma_f32_16x16x32_bf16 v[16:19], v[178:181], v[202:205], v[16:19]
	v_mfma_f32_16x16x32_bf16 v[4:7], v[170:173], v[210:213], v[4:7]
	v_mfma_f32_16x16x32_bf16 v[0:3], v[178:181], v[210:213], v[0:3]
	s_setprio 0
	s_barrier
	s_add_i32 s77, 0, 0x18000
	s_add_i32 s78, 0, 0x1c000
	v_add_u32_e32 v140, s77, v166
	v_add_u32_e32 v178, s78, v166
	ds_read_b128 v[128:131], v140
	ds_read_b128 v[132:135], v140 offset:1024
	ds_read_b128 v[136:139], v140 offset:2048
	ds_read_b128 v[140:143], v140 offset:3072
	ds_read_b128 v[160:163], v178
	ds_read_b128 v[170:173], v178 offset:1024
	ds_read_b128 v[174:177], v178 offset:2048
	ds_read_b128 v[178:181], v178 offset:3072
	s_add_u32 s28, s42, 0x2000
	s_addc_u32 s29, s43, 0
	s_mov_b32 m0, s46
	ds_read_b128 v[182:185], v169 offset:32768
	ds_read_b128 v[186:189], v169 offset:33792
	ds_read_b128 v[190:193], v169 offset:34816
	ds_read_b128 v[194:197], v169 offset:35840
	ds_read_b128 v[198:201], v169 offset:36864
	ds_read_b128 v[202:205], v169 offset:37888
	ds_read_b128 v[206:209], v169 offset:38912
	ds_read_b128 v[210:213], v169 offset:39936
	global_load_lds_dwordx4 v150, s[28:29]
	s_mov_b32 m0, s47
	s_nop 0
	global_load_lds_dwordx4 v146, s[28:29]
	s_nop 0
	s_waitcnt vmcnt(8)
	s_waitcnt lgkmcnt(0)
	s_barrier
	s_setprio 1
	s_waitcnt lgkmcnt(0)
	v_mfma_f32_16x16x32_bf16 v[124:127], v[128:131], v[182:185], v[124:127]
	v_mfma_f32_16x16x32_bf16 v[120:123], v[136:139], v[182:185], v[120:123]
	v_mfma_f32_16x16x32_bf16 v[116:119], v[128:131], v[190:193], v[116:119]
	v_mfma_f32_16x16x32_bf16 v[112:115], v[136:139], v[190:193], v[112:115]
	v_mfma_f32_16x16x32_bf16 v[92:95], v[128:131], v[198:201], v[92:95]
	v_mfma_f32_16x16x32_bf16 v[88:91], v[136:139], v[198:201], v[88:91]
	v_mfma_f32_16x16x32_bf16 v[76:79], v[128:131], v[206:209], v[76:79]
	v_mfma_f32_16x16x32_bf16 v[72:75], v[136:139], v[206:209], v[72:75]
	v_mfma_f32_16x16x32_bf16 v[124:127], v[132:135], v[186:189], v[124:127]
	v_mfma_f32_16x16x32_bf16 v[120:123], v[140:143], v[186:189], v[120:123]
	v_mfma_f32_16x16x32_bf16 v[116:119], v[132:135], v[194:197], v[116:119]
	v_mfma_f32_16x16x32_bf16 v[112:115], v[140:143], v[194:197], v[112:115]
	v_mfma_f32_16x16x32_bf16 v[92:95], v[132:135], v[202:205], v[92:95]
	v_mfma_f32_16x16x32_bf16 v[88:91], v[140:143], v[202:205], v[88:91]
	v_mfma_f32_16x16x32_bf16 v[76:79], v[132:135], v[210:213], v[76:79]
	v_mfma_f32_16x16x32_bf16 v[72:75], v[140:143], v[210:213], v[72:75]
	s_setprio 0
	s_setprio 1
	v_mfma_f32_16x16x32_bf16 v[108:111], v[160:163], v[182:185], v[108:111]
	v_mfma_f32_16x16x32_bf16 v[104:107], v[174:177], v[182:185], v[104:107]
	v_mfma_f32_16x16x32_bf16 v[100:103], v[160:163], v[190:193], v[100:103]
	v_mfma_f32_16x16x32_bf16 v[96:99], v[174:177], v[190:193], v[96:99]
	v_mfma_f32_16x16x32_bf16 v[84:87], v[160:163], v[198:201], v[84:87]
	v_mfma_f32_16x16x32_bf16 v[80:83], v[174:177], v[198:201], v[80:83]
	v_mfma_f32_16x16x32_bf16 v[68:71], v[160:163], v[206:209], v[68:71]
	v_mfma_f32_16x16x32_bf16 v[64:67], v[174:177], v[206:209], v[64:67]
	v_mfma_f32_16x16x32_bf16 v[108:111], v[170:173], v[186:189], v[108:111]
	v_mfma_f32_16x16x32_bf16 v[104:107], v[178:181], v[186:189], v[104:107]
	v_mfma_f32_16x16x32_bf16 v[100:103], v[170:173], v[194:197], v[100:103]
	v_mfma_f32_16x16x32_bf16 v[96:99], v[178:181], v[194:197], v[96:99]
	v_mfma_f32_16x16x32_bf16 v[84:87], v[170:173], v[202:205], v[84:87]
	v_mfma_f32_16x16x32_bf16 v[80:83], v[178:181], v[202:205], v[80:83]
	v_mfma_f32_16x16x32_bf16 v[68:71], v[170:173], v[210:213], v[68:71]
	v_mfma_f32_16x16x32_bf16 v[64:67], v[178:181], v[210:213], v[64:67]
	s_setprio 0
	s_barrier
	s_add_u32 s98, s40, s12
	s_addc_u32 s99, s41, s13
	s_add_i32 s28, s77, s35
	s_mov_b32 m0, s28
	ds_read_b128 v[182:185], v169 offset:49152
	ds_read_b128 v[186:189], v169 offset:50176
	ds_read_b128 v[190:193], v169 offset:51200
	ds_read_b128 v[194:197], v169 offset:52224
	ds_read_b128 v[198:201], v169 offset:53248
	ds_read_b128 v[202:205], v169 offset:54272
	ds_read_b128 v[206:209], v169 offset:55296
	ds_read_b128 v[210:213], v169 offset:56320
	global_load_lds_dwordx4 v148, s[98:99]
	s_add_i32 m0, s28, 0x2000
	s_add_u32 s28, s40, 0x40080
	s_addc_u32 s29, s41, 0
	s_add_i32 s40, s78, s35
	global_load_lds_dwordx4 v144, s[98:99]
	s_mov_b32 m0, s40
	s_nop 0
	global_load_lds_dwordx4 v148, s[28:29]
	s_add_i32 m0, s40, 0x2000
	s_nop 0
	global_load_lds_dwordx4 v144, s[28:29]
	s_mov_b32 m0, s68
	s_nop 0
	global_load_lds_dwordx4 v150, s[38:39]
	s_mov_b32 m0, s69
	s_nop 0
	global_load_lds_dwordx4 v146, s[38:39]
	s_waitcnt vmcnt(8)
	s_waitcnt lgkmcnt(0)
	s_barrier
	s_setprio 1
	s_waitcnt lgkmcnt(0)
	v_mfma_f32_16x16x32_bf16 v[60:63], v[128:131], v[182:185], v[60:63]
	v_mfma_f32_16x16x32_bf16 v[56:59], v[136:139], v[182:185], v[56:59]
	v_mfma_f32_16x16x32_bf16 v[44:47], v[128:131], v[190:193], v[44:47]
	v_mfma_f32_16x16x32_bf16 v[40:43], v[136:139], v[190:193], v[40:43]
	v_mfma_f32_16x16x32_bf16 v[28:31], v[128:131], v[198:201], v[28:31]
	v_mfma_f32_16x16x32_bf16 v[24:27], v[136:139], v[198:201], v[24:27]
	v_mfma_f32_16x16x32_bf16 v[12:15], v[128:131], v[206:209], v[12:15]
	v_mfma_f32_16x16x32_bf16 v[8:11], v[136:139], v[206:209], v[8:11]
	v_mfma_f32_16x16x32_bf16 v[60:63], v[132:135], v[186:189], v[60:63]
	v_mfma_f32_16x16x32_bf16 v[56:59], v[140:143], v[186:189], v[56:59]
	v_mfma_f32_16x16x32_bf16 v[44:47], v[132:135], v[194:197], v[44:47]
	v_mfma_f32_16x16x32_bf16 v[40:43], v[140:143], v[194:197], v[40:43]
	v_mfma_f32_16x16x32_bf16 v[28:31], v[132:135], v[202:205], v[28:31]
	v_mfma_f32_16x16x32_bf16 v[24:27], v[140:143], v[202:205], v[24:27]
	v_mfma_f32_16x16x32_bf16 v[12:15], v[132:135], v[210:213], v[12:15]
	v_mfma_f32_16x16x32_bf16 v[8:11], v[140:143], v[210:213], v[8:11]
	s_setprio 0
	s_setprio 1
	v_mfma_f32_16x16x32_bf16 v[52:55], v[160:163], v[182:185], v[52:55]
	v_mfma_f32_16x16x32_bf16 v[48:51], v[174:177], v[182:185], v[48:51]
	v_mfma_f32_16x16x32_bf16 v[36:39], v[160:163], v[190:193], v[36:39]
	v_mfma_f32_16x16x32_bf16 v[32:35], v[174:177], v[190:193], v[32:35]
	v_mfma_f32_16x16x32_bf16 v[20:23], v[160:163], v[198:201], v[20:23]
	v_mfma_f32_16x16x32_bf16 v[16:19], v[174:177], v[198:201], v[16:19]
	v_mfma_f32_16x16x32_bf16 v[4:7], v[160:163], v[206:209], v[4:7]
	v_mfma_f32_16x16x32_bf16 v[0:3], v[174:177], v[206:209], v[0:3]
	v_mfma_f32_16x16x32_bf16 v[52:55], v[170:173], v[186:189], v[52:55]
	v_mfma_f32_16x16x32_bf16 v[48:51], v[178:181], v[186:189], v[48:51]
	v_mfma_f32_16x16x32_bf16 v[36:39], v[170:173], v[194:197], v[36:39]
	v_mfma_f32_16x16x32_bf16 v[32:35], v[178:181], v[194:197], v[32:35]
	v_mfma_f32_16x16x32_bf16 v[20:23], v[170:173], v[202:205], v[20:23]
	v_mfma_f32_16x16x32_bf16 v[16:19], v[178:181], v[202:205], v[16:19]
	v_mfma_f32_16x16x32_bf16 v[4:7], v[170:173], v[210:213], v[4:7]
	v_mfma_f32_16x16x32_bf16 v[0:3], v[178:181], v[210:213], v[0:3]
	s_setprio 0
	s_barrier
	s_add_i32 s76, s76, 2
	s_add_u32 s74, s74, 0x100
	s_addc_u32 s75, s75, 0
	s_cmp_gt_u32 s76, 13
	s_mov_b64 s[28:29], s[36:37]
	s_cbranch_scc0 .LBB0_568
	s_and_b64 vcc, exec, s[10:11]
	s_cbranch_vccz .LBB0_571

.LBB0_615:
	v_add_u32_e32 v151, s51, v149
	ds_read_b128 v[152:155], v151
	ds_read_b128 v[156:159], v151 offset:1024
	ds_read_b128 v[160:163], v151 offset:2048
	ds_read_b128 v[164:167], v151 offset:3072
	v_add_u32_e32 v151, s56, v149
	ds_read_b128 v[168:171], v151
	ds_read_b128 v[172:175], v151 offset:1024
	ds_read_b128 v[176:179], v151 offset:2048
	ds_read_b128 v[180:183], v151 offset:3072
	s_add_u32 s38, s12, s36
	s_addc_u32 s39, s13, s37
	s_cmp_eq_u32 s63, 60
	s_cselect_b32 s42, s59, s38
	s_cselect_b32 s43, s23, s39
	s_cselect_b32 s40, s60, s61
	s_cselect_b32 s41, s21, s62
	s_add_u32 s38, s42, 0x8000
	s_addc_u32 s39, s43, 0
	s_add_i32 m0, s44, 0xc000
	ds_read_b128 v[184:187], v150
	ds_read_b128 v[188:191], v150 offset:1024
	ds_read_b128 v[192:195], v150 offset:2048
	ds_read_b128 v[196:199], v150 offset:3072
	ds_read_b128 v[200:203], v150 offset:4096
	ds_read_b128 v[204:207], v150 offset:5120
	ds_read_b128 v[208:211], v150 offset:6144
	ds_read_b128 v[212:215], v150 offset:7168
	global_load_lds_dwordx4 v146, s[12:13]
	s_add_i32 m0, s44, 0xe000
	s_nop 0
	global_load_lds_dwordx4 v144, s[12:13]
	s_nop 0
	s_waitcnt vmcnt(8)
	s_waitcnt lgkmcnt(0)
	s_barrier
	s_setprio 1
	s_waitcnt lgkmcnt(0)
	v_mfma_f32_16x16x32_bf16 v[124:127], v[152:155], v[184:187], v[124:127]
	v_mfma_f32_16x16x32_bf16 v[120:123], v[160:163], v[184:187], v[120:123]
	v_mfma_f32_16x16x32_bf16 v[108:111], v[152:155], v[192:195], v[108:111]
	v_mfma_f32_16x16x32_bf16 v[104:107], v[160:163], v[192:195], v[104:107]
	v_mfma_f32_16x16x32_bf16 v[92:95], v[152:155], v[200:203], v[92:95]
	v_mfma_f32_16x16x32_bf16 v[88:91], v[160:163], v[200:203], v[88:91]
	v_mfma_f32_16x16x32_bf16 v[76:79], v[152:155], v[208:211], v[76:79]
	v_mfma_f32_16x16x32_bf16 v[72:75], v[160:163], v[208:211], v[72:75]
	v_mfma_f32_16x16x32_bf16 v[124:127], v[156:159], v[188:191], v[124:127]
	v_mfma_f32_16x16x32_bf16 v[120:123], v[164:167], v[188:191], v[120:123]
	v_mfma_f32_16x16x32_bf16 v[108:111], v[156:159], v[196:199], v[108:111]
	v_mfma_f32_16x16x32_bf16 v[104:107], v[164:167], v[196:199], v[104:107]
	v_mfma_f32_16x16x32_bf16 v[92:95], v[156:159], v[204:207], v[92:95]
	v_mfma_f32_16x16x32_bf16 v[88:91], v[164:167], v[204:207], v[88:91]
	v_mfma_f32_16x16x32_bf16 v[76:79], v[156:159], v[212:215], v[76:79]
	v_mfma_f32_16x16x32_bf16 v[72:75], v[164:167], v[212:215], v[72:75]
	s_setprio 0
	s_setprio 1
	v_mfma_f32_16x16x32_bf16 v[116:119], v[168:171], v[184:187], v[116:119]
	v_mfma_f32_16x16x32_bf16 v[112:115], v[176:179], v[184:187], v[112:115]
	v_mfma_f32_16x16x32_bf16 v[100:103], v[168:171], v[192:195], v[100:103]
	v_mfma_f32_16x16x32_bf16 v[96:99], v[176:179], v[192:195], v[96:99]
	v_mfma_f32_16x16x32_bf16 v[84:87], v[168:171], v[200:203], v[84:87]
	v_mfma_f32_16x16x32_bf16 v[80:83], v[176:179], v[200:203], v[80:83]
	v_mfma_f32_16x16x32_bf16 v[68:71], v[168:171], v[208:211], v[68:71]
	v_mfma_f32_16x16x32_bf16 v[64:67], v[176:179], v[208:211], v[64:67]
	v_mfma_f32_16x16x32_bf16 v[116:119], v[172:175], v[188:191], v[116:119]
	v_mfma_f32_16x16x32_bf16 v[112:115], v[180:183], v[188:191], v[112:115]
	v_mfma_f32_16x16x32_bf16 v[100:103], v[172:175], v[196:199], v[100:103]
	v_mfma_f32_16x16x32_bf16 v[96:99], v[180:183], v[196:199], v[96:99]
	v_mfma_f32_16x16x32_bf16 v[84:87], v[172:175], v[204:207], v[84:87]
	v_mfma_f32_16x16x32_bf16 v[80:83], v[180:183], v[204:207], v[80:83]
	v_mfma_f32_16x16x32_bf16 v[68:71], v[172:175], v[212:215], v[68:71]
	v_mfma_f32_16x16x32_bf16 v[64:67], v[180:183], v[212:215], v[64:67]
	s_setprio 0
	s_barrier
	s_add_i32 s64, s51, s35
	s_mov_b32 m0, s64
	ds_read_b128 v[184:187], v150 offset:16384
	ds_read_b128 v[188:191], v150 offset:17408
	ds_read_b128 v[192:195], v150 offset:18432
	ds_read_b128 v[196:199], v150 offset:19456
	ds_read_b128 v[200:203], v150 offset:20480
	ds_read_b128 v[204:207], v150 offset:21504
	ds_read_b128 v[208:211], v150 offset:22528
	ds_read_b128 v[212:215], v150 offset:23552
	global_load_lds_dwordx4 v130, s[40:41]
	s_add_i32 m0, s64, 0x2000
	s_add_u32 s64, s40, 0x100000
	v_lshl_add_u64 v[218:219], s[40:41], 0, v[134:135]
	s_addc_u32 s65, s41, 0
	s_add_i32 s66, s56, s35
	global_load_lds_dwordx4 v[218:219], off
	s_mov_b32 m0, s66
	s_nop 0
	global_load_lds_dwordx4 v130, s[64:65]
	s_add_i32 m0, s66, 0x2000
	s_nop 0
	global_load_lds_dwordx4 v134, s[64:65]
	s_mov_b32 m0, s44
	s_nop 0
	global_load_lds_dwordx4 v128, s[42:43]
	s_mov_b32 m0, s45
	s_nop 0
	global_load_lds_dwordx4 v132, s[42:43]
	s_waitcnt vmcnt(8)
	s_waitcnt lgkmcnt(0)
	s_barrier
	s_setprio 1
	s_waitcnt lgkmcnt(0)
	v_mfma_f32_16x16x32_bf16 v[60:63], v[152:155], v[184:187], v[60:63]
	v_mfma_f32_16x16x32_bf16 v[56:59], v[160:163], v[184:187], v[56:59]
	v_mfma_f32_16x16x32_bf16 v[44:47], v[152:155], v[192:195], v[44:47]
	v_mfma_f32_16x16x32_bf16 v[40:43], v[160:163], v[192:195], v[40:43]
	v_mfma_f32_16x16x32_bf16 v[28:31], v[152:155], v[200:203], v[28:31]
	v_mfma_f32_16x16x32_bf16 v[24:27], v[160:163], v[200:203], v[24:27]
	v_mfma_f32_16x16x32_bf16 v[12:15], v[152:155], v[208:211], v[12:15]
	v_mfma_f32_16x16x32_bf16 v[8:11], v[160:163], v[208:211], v[8:11]
	v_mfma_f32_16x16x32_bf16 v[60:63], v[156:159], v[188:191], v[60:63]
	v_mfma_f32_16x16x32_bf16 v[56:59], v[164:167], v[188:191], v[56:59]
	v_mfma_f32_16x16x32_bf16 v[44:47], v[156:159], v[196:199], v[44:47]
	v_mfma_f32_16x16x32_bf16 v[40:43], v[164:167], v[196:199], v[40:43]
	v_mfma_f32_16x16x32_bf16 v[28:31], v[156:159], v[204:207], v[28:31]
	v_mfma_f32_16x16x32_bf16 v[24:27], v[164:167], v[204:207], v[24:27]
	v_mfma_f32_16x16x32_bf16 v[12:15], v[156:159], v[212:215], v[12:15]
	v_mfma_f32_16x16x32_bf16 v[8:11], v[164:167], v[212:215], v[8:11]
	s_setprio 0
	s_setprio 1
	v_mfma_f32_16x16x32_bf16 v[52:55], v[168:171], v[184:187], v[52:55]
	v_mfma_f32_16x16x32_bf16 v[48:51], v[176:179], v[184:187], v[48:51]
	v_mfma_f32_16x16x32_bf16 v[36:39], v[168:171], v[192:195], v[36:39]
	v_mfma_f32_16x16x32_bf16 v[32:35], v[176:179], v[192:195], v[32:35]
	v_mfma_f32_16x16x32_bf16 v[20:23], v[168:171], v[200:203], v[20:23]
	v_mfma_f32_16x16x32_bf16 v[16:19], v[176:179], v[200:203], v[16:19]
	v_mfma_f32_16x16x32_bf16 v[4:7], v[168:171], v[208:211], v[4:7]
	v_mfma_f32_16x16x32_bf16 v[0:3], v[176:179], v[208:211], v[0:3]
	v_mfma_f32_16x16x32_bf16 v[52:55], v[172:175], v[188:191], v[52:55]
	v_mfma_f32_16x16x32_bf16 v[48:51], v[180:183], v[188:191], v[48:51]
	v_mfma_f32_16x16x32_bf16 v[36:39], v[172:175], v[196:199], v[36:39]
	v_mfma_f32_16x16x32_bf16 v[32:35], v[180:183], v[196:199], v[32:35]
	v_mfma_f32_16x16x32_bf16 v[20:23], v[172:175], v[204:207], v[20:23]
	v_mfma_f32_16x16x32_bf16 v[16:19], v[180:183], v[204:207], v[16:19]
	v_mfma_f32_16x16x32_bf16 v[4:7], v[172:175], v[212:215], v[4:7]
	v_mfma_f32_16x16x32_bf16 v[0:3], v[180:183], v[212:215], v[0:3]
	s_setprio 0
	s_barrier
	s_add_i32 s64, 0, 0x18000
	v_add_u32_e32 v151, s64, v149
	s_add_i32 s65, 0, 0x1c000
	ds_read_b128 v[152:155], v151
	ds_read_b128 v[156:159], v151 offset:1024
	ds_read_b128 v[160:163], v151 offset:2048
	ds_read_b128 v[164:167], v151 offset:3072
	v_add_u32_e32 v151, s65, v149
	ds_read_b128 v[168:171], v151
	ds_read_b128 v[172:175], v151 offset:1024
	ds_read_b128 v[176:179], v151 offset:2048
	ds_read_b128 v[180:183], v151 offset:3072
	s_add_u32 s42, s42, 0x2000
	s_addc_u32 s43, s43, 0
	s_mov_b32 m0, s46
	ds_read_b128 v[184:187], v150 offset:32768
	ds_read_b128 v[188:191], v150 offset:33792
	ds_read_b128 v[192:195], v150 offset:34816
	ds_read_b128 v[196:199], v150 offset:35840
	ds_read_b128 v[200:203], v150 offset:36864
	ds_read_b128 v[204:207], v150 offset:37888
	ds_read_b128 v[208:211], v150 offset:38912
	ds_read_b128 v[212:215], v150 offset:39936
	global_load_lds_dwordx4 v128, s[42:43]
	s_mov_b32 m0, s47
	s_nop 0
	global_load_lds_dwordx4 v132, s[42:43]
	s_nop 0
	s_waitcnt vmcnt(8)
	s_waitcnt lgkmcnt(0)
	s_barrier
	s_setprio 1
	s_waitcnt lgkmcnt(0)
	v_mfma_f32_16x16x32_bf16 v[124:127], v[152:155], v[184:187], v[124:127]
	v_mfma_f32_16x16x32_bf16 v[120:123], v[160:163], v[184:187], v[120:123]
	v_mfma_f32_16x16x32_bf16 v[108:111], v[152:155], v[192:195], v[108:111]
	v_mfma_f32_16x16x32_bf16 v[104:107], v[160:163], v[192:195], v[104:107]
	v_mfma_f32_16x16x32_bf16 v[92:95], v[152:155], v[200:203], v[92:95]
	v_mfma_f32_16x16x32_bf16 v[88:91], v[160:163], v[200:203], v[88:91]
	v_mfma_f32_16x16x32_bf16 v[76:79], v[152:155], v[208:211], v[76:79]
	v_mfma_f32_16x16x32_bf16 v[72:75], v[160:163], v[208:211], v[72:75]
	v_mfma_f32_16x16x32_bf16 v[124:127], v[156:159], v[188:191], v[124:127]
	v_mfma_f32_16x16x32_bf16 v[120:123], v[164:167], v[188:191], v[120:123]
	v_mfma_f32_16x16x32_bf16 v[108:111], v[156:159], v[196:199], v[108:111]
	v_mfma_f32_16x16x32_bf16 v[104:107], v[164:167], v[196:199], v[104:107]
	v_mfma_f32_16x16x32_bf16 v[92:95], v[156:159], v[204:207], v[92:95]
	v_mfma_f32_16x16x32_bf16 v[88:91], v[164:167], v[204:207], v[88:91]
	v_mfma_f32_16x16x32_bf16 v[76:79], v[156:159], v[212:215], v[76:79]
	v_mfma_f32_16x16x32_bf16 v[72:75], v[164:167], v[212:215], v[72:75]
	s_setprio 0
	s_setprio 1
	v_mfma_f32_16x16x32_bf16 v[116:119], v[168:171], v[184:187], v[116:119]
	v_mfma_f32_16x16x32_bf16 v[112:115], v[176:179], v[184:187], v[112:115]
	v_mfma_f32_16x16x32_bf16 v[100:103], v[168:171], v[192:195], v[100:103]
	v_mfma_f32_16x16x32_bf16 v[96:99], v[176:179], v[192:195], v[96:99]
	v_mfma_f32_16x16x32_bf16 v[84:87], v[168:171], v[200:203], v[84:87]
	v_mfma_f32_16x16x32_bf16 v[80:83], v[176:179], v[200:203], v[80:83]
	v_mfma_f32_16x16x32_bf16 v[68:71], v[168:171], v[208:211], v[68:71]
	v_mfma_f32_16x16x32_bf16 v[64:67], v[176:179], v[208:211], v[64:67]
	v_mfma_f32_16x16x32_bf16 v[116:119], v[172:175], v[188:191], v[116:119]
	v_mfma_f32_16x16x32_bf16 v[112:115], v[180:183], v[188:191], v[112:115]
	v_mfma_f32_16x16x32_bf16 v[100:103], v[172:175], v[196:199], v[100:103]
	v_mfma_f32_16x16x32_bf16 v[96:99], v[180:183], v[196:199], v[96:99]
	v_mfma_f32_16x16x32_bf16 v[84:87], v[172:175], v[204:207], v[84:87]
	v_mfma_f32_16x16x32_bf16 v[80:83], v[180:183], v[204:207], v[80:83]
	v_mfma_f32_16x16x32_bf16 v[68:71], v[172:175], v[212:215], v[68:71]
	v_mfma_f32_16x16x32_bf16 v[64:67], v[180:183], v[212:215], v[64:67]
	s_setprio 0
	s_barrier
	s_add_u32 s98, s40, s16
	s_addc_u32 s99, s41, s17
	s_add_i32 s42, s64, s35
	s_mov_b32 m0, s42
	ds_read_b128 v[184:187], v150 offset:49152
	ds_read_b128 v[188:191], v150 offset:50176
	ds_read_b128 v[192:195], v150 offset:51200
	ds_read_b128 v[196:199], v150 offset:52224
	ds_read_b128 v[200:203], v150 offset:53248
	ds_read_b128 v[204:207], v150 offset:54272
	ds_read_b128 v[208:211], v150 offset:55296
	ds_read_b128 v[212:215], v150 offset:56320
	global_load_lds_dwordx4 v130, s[98:99]
	s_add_i32 m0, s42, 0x2000
	s_add_u32 s40, s40, 0x100080
	v_lshl_add_u64 v[216:217], v[218:219], 0, s[16:17]
	s_addc_u32 s41, s41, 0
	s_add_i32 s42, s65, s35
	global_load_lds_dwordx4 v[216:217], off
	s_mov_b32 m0, s42
	s_nop 0
	global_load_lds_dwordx4 v130, s[40:41]
	s_add_i32 m0, s42, 0x2000
	s_nop 0
	global_load_lds_dwordx4 v134, s[40:41]
	s_mov_b32 m0, s48
	s_nop 0
	global_load_lds_dwordx4 v128, s[38:39]
	s_mov_b32 m0, s49
	s_nop 0
	global_load_lds_dwordx4 v132, s[38:39]
	s_waitcnt vmcnt(8)
	s_waitcnt lgkmcnt(0)
	s_barrier
	s_setprio 1
	s_waitcnt lgkmcnt(0)
	v_mfma_f32_16x16x32_bf16 v[60:63], v[152:155], v[184:187], v[60:63]
	v_mfma_f32_16x16x32_bf16 v[56:59], v[160:163], v[184:187], v[56:59]
	v_mfma_f32_16x16x32_bf16 v[44:47], v[152:155], v[192:195], v[44:47]
	v_mfma_f32_16x16x32_bf16 v[40:43], v[160:163], v[192:195], v[40:43]
	v_mfma_f32_16x16x32_bf16 v[28:31], v[152:155], v[200:203], v[28:31]
	v_mfma_f32_16x16x32_bf16 v[24:27], v[160:163], v[200:203], v[24:27]
	v_mfma_f32_16x16x32_bf16 v[12:15], v[152:155], v[208:211], v[12:15]
	v_mfma_f32_16x16x32_bf16 v[8:11], v[160:163], v[208:211], v[8:11]
	v_mfma_f32_16x16x32_bf16 v[60:63], v[156:159], v[188:191], v[60:63]
	v_mfma_f32_16x16x32_bf16 v[56:59], v[164:167], v[188:191], v[56:59]
	v_mfma_f32_16x16x32_bf16 v[44:47], v[156:159], v[196:199], v[44:47]
	v_mfma_f32_16x16x32_bf16 v[40:43], v[164:167], v[196:199], v[40:43]
	v_mfma_f32_16x16x32_bf16 v[28:31], v[156:159], v[204:207], v[28:31]
	v_mfma_f32_16x16x32_bf16 v[24:27], v[164:167], v[204:207], v[24:27]
	v_mfma_f32_16x16x32_bf16 v[12:15], v[156:159], v[212:215], v[12:15]
	v_mfma_f32_16x16x32_bf16 v[8:11], v[164:167], v[212:215], v[8:11]
	s_setprio 0
	s_setprio 1
	v_mfma_f32_16x16x32_bf16 v[52:55], v[168:171], v[184:187], v[52:55]
	v_mfma_f32_16x16x32_bf16 v[48:51], v[176:179], v[184:187], v[48:51]
	v_mfma_f32_16x16x32_bf16 v[36:39], v[168:171], v[192:195], v[36:39]
	v_mfma_f32_16x16x32_bf16 v[32:35], v[176:179], v[192:195], v[32:35]
	v_mfma_f32_16x16x32_bf16 v[20:23], v[168:171], v[200:203], v[20:23]
	v_mfma_f32_16x16x32_bf16 v[16:19], v[176:179], v[200:203], v[16:19]
	v_mfma_f32_16x16x32_bf16 v[4:7], v[168:171], v[208:211], v[4:7]
	v_mfma_f32_16x16x32_bf16 v[0:3], v[176:179], v[208:211], v[0:3]
	v_mfma_f32_16x16x32_bf16 v[52:55], v[172:175], v[188:191], v[52:55]
	v_mfma_f32_16x16x32_bf16 v[48:51], v[180:183], v[188:191], v[48:51]
	v_mfma_f32_16x16x32_bf16 v[36:39], v[172:175], v[196:199], v[36:39]
	v_mfma_f32_16x16x32_bf16 v[32:35], v[180:183], v[196:199], v[32:35]
	v_mfma_f32_16x16x32_bf16 v[20:23], v[172:175], v[204:207], v[20:23]
	v_mfma_f32_16x16x32_bf16 v[16:19], v[180:183], v[204:207], v[16:19]
	v_mfma_f32_16x16x32_bf16 v[4:7], v[172:175], v[212:215], v[4:7]
	v_mfma_f32_16x16x32_bf16 v[0:3], v[180:183], v[212:215], v[0:3]
	s_setprio 0
	s_barrier
	s_add_i32 s63, s63, 2
	s_add_u32 s61, s61, 0x100
	s_addc_u32 s62, s62, 0
	s_add_u32 s36, s36, 0x10000
	s_addc_u32 s37, s37, 0
	v_lshl_add_u64 v[146:147], v[146:147], 0, s[18:19]
	s_cmp_gt_u32 s63, 61
	v_lshl_add_u64 v[144:145], v[144:145], 0, s[18:19]
	s_cbranch_scc0 .LBB0_615
	s_andn2_b64 vcc, exec, s[4:5]
	s_cbranch_vccnz .LBB0_607
	v_mov_b32_e32 v0, 0
	s_mov_b32 s8, s20
	s_mov_b32 s6, s22
	s_mov_b64 s[10:11], s[28:29]
	s_mov_b64 s[12:13], s[26:27]
	s_mov_b32 s50, s57
	v_mov_b32_e32 v1, v0
	v_mov_b32_e32 v2, v0
	v_mov_b32_e32 v3, v0
	v_mov_b32_e32 v4, v0
	v_mov_b32_e32 v5, v0
	v_mov_b32_e32 v6, v0
	v_mov_b32_e32 v7, v0
	v_mov_b32_e32 v16, v0
	v_mov_b32_e32 v17, v0
	v_mov_b32_e32 v18, v0
	v_mov_b32_e32 v19, v0
	v_mov_b32_e32 v20, v0
	v_mov_b32_e32 v21, v0
	v_mov_b32_e32 v22, v0
	v_mov_b32_e32 v23, v0
	v_mov_b32_e32 v32, v0
	v_mov_b32_e32 v33, v0
	v_mov_b32_e32 v34, v0
	v_mov_b32_e32 v35, v0
	v_mov_b32_e32 v36, v0
	v_mov_b32_e32 v37, v0
	v_mov_b32_e32 v38, v0
	v_mov_b32_e32 v39, v0
	v_mov_b32_e32 v48, v0
	v_mov_b32_e32 v49, v0
	v_mov_b32_e32 v50, v0
	v_mov_b32_e32 v51, v0
	v_mov_b32_e32 v52, v0
	v_mov_b32_e32 v53, v0
	v_mov_b32_e32 v54, v0
	v_mov_b32_e32 v55, v0
	v_mov_b32_e32 v8, v0
	v_mov_b32_e32 v9, v0
	v_mov_b32_e32 v10, v0
	v_mov_b32_e32 v11, v0
	v_mov_b32_e32 v12, v0
	v_mov_b32_e32 v13, v0
	v_mov_b32_e32 v14, v0
	v_mov_b32_e32 v15, v0
	v_mov_b32_e32 v24, v0
	v_mov_b32_e32 v25, v0
	v_mov_b32_e32 v26, v0
	v_mov_b32_e32 v27, v0
	v_mov_b32_e32 v28, v0
	v_mov_b32_e32 v29, v0
	v_mov_b32_e32 v30, v0
	v_mov_b32_e32 v31, v0
	v_mov_b32_e32 v40, v0
	v_mov_b32_e32 v41, v0
	v_mov_b32_e32 v42, v0
	v_mov_b32_e32 v43, v0
	v_mov_b32_e32 v44, v0
	v_mov_b32_e32 v45, v0
	v_mov_b32_e32 v46, v0
	v_mov_b32_e32 v47, v0
	v_mov_b32_e32 v56, v0
	v_mov_b32_e32 v57, v0
	v_mov_b32_e32 v58, v0
	v_mov_b32_e32 v59, v0
	v_mov_b32_e32 v60, v0
	v_mov_b32_e32 v61, v0
	v_mov_b32_e32 v62, v0
	v_mov_b32_e32 v63, v0
	v_mov_b32_e32 v64, v0
	v_mov_b32_e32 v65, v0
	v_mov_b32_e32 v66, v0
	v_mov_b32_e32 v67, v0
	v_mov_b32_e32 v68, v0
	v_mov_b32_e32 v69, v0
	v_mov_b32_e32 v70, v0
	v_mov_b32_e32 v71, v0
	v_mov_b32_e32 v80, v0
	v_mov_b32_e32 v81, v0
	v_mov_b32_e32 v82, v0
	v_mov_b32_e32 v83, v0
	v_mov_b32_e32 v84, v0
	v_mov_b32_e32 v85, v0
	v_mov_b32_e32 v86, v0
	v_mov_b32_e32 v87, v0
	v_mov_b32_e32 v96, v0
	v_mov_b32_e32 v97, v0
	v_mov_b32_e32 v98, v0
	v_mov_b32_e32 v99, v0
	v_mov_b32_e32 v100, v0
	v_mov_b32_e32 v101, v0
	v_mov_b32_e32 v102, v0
	v_mov_b32_e32 v103, v0
	v_mov_b32_e32 v112, v0
	v_mov_b32_e32 v113, v0
	v_mov_b32_e32 v114, v0
	v_mov_b32_e32 v115, v0
	v_mov_b32_e32 v116, v0
	v_mov_b32_e32 v117, v0
	v_mov_b32_e32 v118, v0
	v_mov_b32_e32 v119, v0
	v_mov_b32_e32 v72, v0
	v_mov_b32_e32 v73, v0
	v_mov_b32_e32 v74, v0
	v_mov_b32_e32 v75, v0
	v_mov_b32_e32 v76, v0
	v_mov_b32_e32 v77, v0
	v_mov_b32_e32 v78, v0
	v_mov_b32_e32 v79, v0
	v_mov_b32_e32 v88, v0
	v_mov_b32_e32 v89, v0
	v_mov_b32_e32 v90, v0
	v_mov_b32_e32 v91, v0
	v_mov_b32_e32 v92, v0
	v_mov_b32_e32 v93, v0
	v_mov_b32_e32 v94, v0
	v_mov_b32_e32 v95, v0
	v_mov_b32_e32 v104, v0
	v_mov_b32_e32 v105, v0
	v_mov_b32_e32 v106, v0
	v_mov_b32_e32 v107, v0
	v_mov_b32_e32 v108, v0
	v_mov_b32_e32 v109, v0
	v_mov_b32_e32 v110, v0
	v_mov_b32_e32 v111, v0
	v_mov_b32_e32 v120, v0
	v_mov_b32_e32 v121, v0
	v_mov_b32_e32 v122, v0
	v_mov_b32_e32 v123, v0
	v_mov_b32_e32 v124, v0
	v_mov_b32_e32 v125, v0
	v_mov_b32_e32 v126, v0
	v_mov_b32_e32 v127, v0
	s_branch .LBB0_607
